# removed the 64 s_nop 2 behind the PEER u-phase dot chains (no consumer of a dot result within 3 wait states); u phase is VALU-issue bound after the table layout change
# speedup vs baseline: 1.0586x; 1.0031x over previous
; DI float dot16(const unsigned (&a)[8], u32x4 b0, u32x4 b1) {
;     float acc;
;     asm volatile("v_dot2_f32_bf16 %0, %1, %9, 0\n\tv_dot2_f32_bf16 %0, %2, %10, %0\n\tv_dot2_f32_bf16 %0, %3, %11, %0\n\tv_dot2_f32_bf16 %0, %4, %12, %0\n\t"
;                  "v_dot2_f32_bf16 %0, %5, %13, %0\n\tv_dot2_f32_bf16 %0, %6, %14, %0\n\tv_dot2_f32_bf16 %0, %7, %15, %0\n\tv_dot2_f32_bf16 %0, %8, %16, %0\n\ts_nop 2"
;                  : "=&v"(acc)
;                  : "v"(a[0]), "v"(a[1]), "v"(a[2]), "v"(a[3]), "v"(a[4]), "v"(a[5]), "v"(a[6]), "v"(a[7]),
;                    "v"(b0.x), "v"(b0.y), "v"(b0.z), "v"(b0.w), "v"(b1.x), "v"(b1.y), "v"(b1.z), "v"(b1.w));
;     return acc;
; }
; DI float dot_fp8_row(u32x4 u, u32x4 xa, u32x4 xb) {
;     unsigned a[8];
; #pragma unroll
;     for (int j = 0; j < 4; ++j) {
;         a[2 * j] = __builtin_bit_cast(unsigned, __builtin_amdgcn_cvt_scalef32_pk_bf16_fp8(u[j], 1.0f, false));
;         a[2 * j + 1] = __builtin_bit_cast(unsigned, __builtin_amdgcn_cvt_scalef32_pk_bf16_fp8(u[j], 1.0f, true));
;     }
;     return dot16(a, xa, xb);
; }
.LBB0_529:
	s_or_b64 exec, exec, s[18:19]
	s_setprio 1
	v_cvt_scalef32_pk_bf16_fp8 v190, v7, 1.0
	v_cvt_scalef32_pk_bf16_fp8 v188, v6, 1.0
	v_cvt_scalef32_pk_bf16_fp8 v189, v6, 1.0 op_sel:[1,0,0]
	v_cvt_scalef32_pk_bf16_fp8 v191, v7, 1.0 op_sel:[1,0,0]
	v_cvt_scalef32_pk_bf16_fp8 v211, v8, 1.0
	v_cvt_scalef32_pk_bf16_fp8 v212, v8, 1.0 op_sel:[1,0,0]
	v_cvt_scalef32_pk_bf16_fp8 v213, v9, 1.0
	v_cvt_scalef32_pk_bf16_fp8 v214, v9, 1.0 op_sel:[1,0,0]
	v_dot2_f32_bf16 v215, v188, v66, 0
	v_dot2_f32_bf16 v215, v189, v67, v215
	v_dot2_f32_bf16 v215, v190, v68, v215
	v_dot2_f32_bf16 v215, v191, v69, v215
	v_dot2_f32_bf16 v215, v211, v70, v215
	v_dot2_f32_bf16 v215, v212, v71, v215
	v_dot2_f32_bf16 v215, v213, v72, v215
	v_dot2_f32_bf16 v215, v214, v73, v215
	v_cvt_scalef32_pk_bf16_fp8 v190, v3, 1.0
	v_cvt_scalef32_pk_bf16_fp8 v188, v2, 1.0
	v_cvt_scalef32_pk_bf16_fp8 v189, v2, 1.0 op_sel:[1,0,0]
	v_cvt_scalef32_pk_bf16_fp8 v191, v3, 1.0 op_sel:[1,0,0]
	v_cvt_scalef32_pk_bf16_fp8 v211, v4, 1.0
	v_cvt_scalef32_pk_bf16_fp8 v212, v4, 1.0 op_sel:[1,0,0]
	v_cvt_scalef32_pk_bf16_fp8 v213, v5, 1.0
	v_cvt_scalef32_pk_bf16_fp8 v214, v5, 1.0 op_sel:[1,0,0]
	v_dot2_f32_bf16 v216, v188, v66, 0
	v_dot2_f32_bf16 v216, v189, v67, v216
	v_dot2_f32_bf16 v216, v190, v68, v216
	v_dot2_f32_bf16 v216, v191, v69, v216
	v_dot2_f32_bf16 v216, v211, v70, v216
	v_dot2_f32_bf16 v216, v212, v71, v216
	v_dot2_f32_bf16 v216, v213, v72, v216
	v_dot2_f32_bf16 v216, v214, v73, v216
	v_cvt_scalef32_pk_bf16_fp8 v190, v15, 1.0
	v_cvt_scalef32_pk_bf16_fp8 v188, v14, 1.0
	v_cvt_scalef32_pk_bf16_fp8 v189, v14, 1.0 op_sel:[1,0,0]
	v_cvt_scalef32_pk_bf16_fp8 v191, v15, 1.0 op_sel:[1,0,0]
	v_cvt_scalef32_pk_bf16_fp8 v211, v16, 1.0
	v_cvt_scalef32_pk_bf16_fp8 v212, v16, 1.0 op_sel:[1,0,0]
	v_cvt_scalef32_pk_bf16_fp8 v213, v17, 1.0
	v_cvt_scalef32_pk_bf16_fp8 v214, v17, 1.0 op_sel:[1,0,0]
	v_dot2_f32_bf16 v217, v188, v66, 0
	v_dot2_f32_bf16 v217, v189, v67, v217
	v_dot2_f32_bf16 v217, v190, v68, v217
	v_dot2_f32_bf16 v217, v191, v69, v217
	v_dot2_f32_bf16 v217, v211, v70, v217
	v_dot2_f32_bf16 v217, v212, v71, v217
	v_dot2_f32_bf16 v217, v213, v72, v217
	v_dot2_f32_bf16 v217, v214, v73, v217
	v_cvt_scalef32_pk_bf16_fp8 v190, v11, 1.0
	v_cvt_scalef32_pk_bf16_fp8 v188, v10, 1.0
	v_cvt_scalef32_pk_bf16_fp8 v189, v10, 1.0 op_sel:[1,0,0]
	v_cvt_scalef32_pk_bf16_fp8 v191, v11, 1.0 op_sel:[1,0,0]
	v_cvt_scalef32_pk_bf16_fp8 v211, v12, 1.0
	v_cvt_scalef32_pk_bf16_fp8 v212, v12, 1.0 op_sel:[1,0,0]
	v_cvt_scalef32_pk_bf16_fp8 v213, v13, 1.0
	v_cvt_scalef32_pk_bf16_fp8 v214, v13, 1.0 op_sel:[1,0,0]
	v_dot2_f32_bf16 v218, v188, v66, 0
	v_dot2_f32_bf16 v218, v189, v67, v218
	v_dot2_f32_bf16 v218, v190, v68, v218
	v_dot2_f32_bf16 v218, v191, v69, v218
	v_dot2_f32_bf16 v218, v211, v70, v218
	v_dot2_f32_bf16 v218, v212, v71, v218
	v_dot2_f32_bf16 v218, v213, v72, v218
	v_dot2_f32_bf16 v218, v214, v73, v218
	v_cvt_scalef32_pk_bf16_fp8 v190, v23, 1.0
	v_cvt_scalef32_pk_bf16_fp8 v188, v22, 1.0
	v_cvt_scalef32_pk_bf16_fp8 v189, v22, 1.0 op_sel:[1,0,0]
	v_cvt_scalef32_pk_bf16_fp8 v191, v23, 1.0 op_sel:[1,0,0]
	v_cvt_scalef32_pk_bf16_fp8 v211, v24, 1.0
	v_cvt_scalef32_pk_bf16_fp8 v212, v24, 1.0 op_sel:[1,0,0]
	v_cvt_scalef32_pk_bf16_fp8 v213, v25, 1.0
	v_cvt_scalef32_pk_bf16_fp8 v214, v25, 1.0 op_sel:[1,0,0]
	v_dot2_f32_bf16 v219, v188, v66, 0
	v_dot2_f32_bf16 v219, v189, v67, v219
	v_dot2_f32_bf16 v219, v190, v68, v219
	v_dot2_f32_bf16 v219, v191, v69, v219
	v_dot2_f32_bf16 v219, v211, v70, v219
	v_dot2_f32_bf16 v219, v212, v71, v219
	v_dot2_f32_bf16 v219, v213, v72, v219
	v_dot2_f32_bf16 v219, v214, v73, v219
	v_cvt_scalef32_pk_bf16_fp8 v190, v19, 1.0
	v_cvt_scalef32_pk_bf16_fp8 v188, v18, 1.0
	v_cvt_scalef32_pk_bf16_fp8 v189, v18, 1.0 op_sel:[1,0,0]
	v_cvt_scalef32_pk_bf16_fp8 v191, v19, 1.0 op_sel:[1,0,0]
	v_cvt_scalef32_pk_bf16_fp8 v211, v20, 1.0
	v_cvt_scalef32_pk_bf16_fp8 v212, v20, 1.0 op_sel:[1,0,0]
	v_cvt_scalef32_pk_bf16_fp8 v213, v21, 1.0
	v_cvt_scalef32_pk_bf16_fp8 v214, v21, 1.0 op_sel:[1,0,0]
	v_dot2_f32_bf16 v220, v188, v66, 0
	v_dot2_f32_bf16 v220, v189, v67, v220
	v_dot2_f32_bf16 v220, v190, v68, v220
	v_dot2_f32_bf16 v220, v191, v69, v220
	v_dot2_f32_bf16 v220, v211, v70, v220
	v_dot2_f32_bf16 v220, v212, v71, v220
	v_dot2_f32_bf16 v220, v213, v72, v220
	v_dot2_f32_bf16 v220, v214, v73, v220
	v_cvt_scalef32_pk_bf16_fp8 v190, v31, 1.0
	v_cvt_scalef32_pk_bf16_fp8 v188, v30, 1.0
	v_cvt_scalef32_pk_bf16_fp8 v189, v30, 1.0 op_sel:[1,0,0]
	v_cvt_scalef32_pk_bf16_fp8 v191, v31, 1.0 op_sel:[1,0,0]
	v_cvt_scalef32_pk_bf16_fp8 v211, v32, 1.0
	v_cvt_scalef32_pk_bf16_fp8 v212, v32, 1.0 op_sel:[1,0,0]
	v_cvt_scalef32_pk_bf16_fp8 v213, v33, 1.0
	v_cvt_scalef32_pk_bf16_fp8 v214, v33, 1.0 op_sel:[1,0,0]
	v_dot2_f32_bf16 v221, v188, v66, 0
	v_dot2_f32_bf16 v221, v189, v67, v221
	v_dot2_f32_bf16 v221, v190, v68, v221
	v_dot2_f32_bf16 v221, v191, v69, v221
	v_dot2_f32_bf16 v221, v211, v70, v221
	v_dot2_f32_bf16 v221, v212, v71, v221
	v_dot2_f32_bf16 v221, v213, v72, v221
	v_dot2_f32_bf16 v221, v214, v73, v221
	v_cvt_scalef32_pk_bf16_fp8 v190, v27, 1.0
	v_cvt_scalef32_pk_bf16_fp8 v188, v26, 1.0
	v_cvt_scalef32_pk_bf16_fp8 v189, v26, 1.0 op_sel:[1,0,0]
	v_cvt_scalef32_pk_bf16_fp8 v191, v27, 1.0 op_sel:[1,0,0]
	v_cvt_scalef32_pk_bf16_fp8 v211, v28, 1.0
	v_cvt_scalef32_pk_bf16_fp8 v212, v28, 1.0 op_sel:[1,0,0]
	v_cvt_scalef32_pk_bf16_fp8 v214, v29, 1.0
	v_cvt_scalef32_pk_bf16_fp8 v222, v29, 1.0 op_sel:[1,0,0]
	v_dot2_f32_bf16 v223, v188, v66, 0
	v_dot2_f32_bf16 v223, v189, v67, v223
	v_dot2_f32_bf16 v223, v190, v68, v223
	v_dot2_f32_bf16 v223, v191, v69, v223
	v_dot2_f32_bf16 v223, v211, v70, v223
	v_dot2_f32_bf16 v223, v212, v71, v223
	v_dot2_f32_bf16 v223, v214, v72, v223
	v_dot2_f32_bf16 v223, v222, v73, v223
	v_cndmask_b32_e64 v190, v216, v220, s[12:13]
	ds_bpermute_b32 v190, v193, v190
	v_cndmask_b32_e64 v191, v217, v221, s[12:13]
	v_cndmask_b32_e64 v213, v215, v219, s[12:13]
	ds_bpermute_b32 v191, v193, v191
	v_cndmask_b32_e64 v211, v218, v223, s[12:13]
	ds_bpermute_b32 v213, v193, v213
	ds_bpermute_b32 v211, v193, v211
	v_cndmask_b32_e64 v189, v220, v216, s[12:13]
	s_waitcnt lgkmcnt(3)
; DI float dot16(const unsigned (&a)[8], u32x4 b0, u32x4 b1) {
;     float acc;
;     asm volatile("v_dot2_f32_bf16 %0, %1, %9, 0\n\tv_dot2_f32_bf16 %0, %2, %10, %0\n\tv_dot2_f32_bf16 %0, %3, %11, %0\n\tv_dot2_f32_bf16 %0, %4, %12, %0\n\t"
;                  "v_dot2_f32_bf16 %0, %5, %13, %0\n\tv_dot2_f32_bf16 %0, %6, %14, %0\n\tv_dot2_f32_bf16 %0, %7, %15, %0\n\tv_dot2_f32_bf16 %0, %8, %16, %0\n\ts_nop 2"
;                  : "=&v"(acc)
;                  : "v"(a[0]), "v"(a[1]), "v"(a[2]), "v"(a[3]), "v"(a[4]), "v"(a[5]), "v"(a[6]), "v"(a[7]),
;                    "v"(b0.x), "v"(b0.y), "v"(b0.z), "v"(b0.w), "v"(b1.x), "v"(b1.y), "v"(b1.z), "v"(b1.w));
;     return acc;
; }
; DI float dot_fp8_row(u32x4 u, u32x4 xa, u32x4 xb) {
;     unsigned a[8];
; #pragma unroll
;     for (int j = 0; j < 4; ++j) {
;         a[2 * j] = __builtin_bit_cast(unsigned, __builtin_amdgcn_cvt_scalef32_pk_bf16_fp8(u[j], 1.0f, false));
;         a[2 * j + 1] = __builtin_bit_cast(unsigned, __builtin_amdgcn_cvt_scalef32_pk_bf16_fp8(u[j], 1.0f, true));
;     }
;     return dot16(a, xa, xb);
; }
	v_add_f32_e32 v189, v189, v190
	v_cndmask_b32_e64 v190, v221, v217, s[12:13]
	v_cndmask_b32_e64 v188, v219, v215, s[12:13]
	s_waitcnt lgkmcnt(2)
	v_add_f32_e32 v190, v190, v191
	v_cndmask_b32_e64 v191, v223, v218, s[12:13]
	s_waitcnt lgkmcnt(1)
	v_add_f32_e32 v188, v188, v213
	s_waitcnt lgkmcnt(0)
	v_add_f32_e32 v191, v191, v211
	v_cndmask_b32_e64 v211, v188, v190, s[14:15]
	v_cndmask_b32_e64 v212, v189, v191, s[14:15]
	ds_bpermute_b32 v211, v194, v211
	ds_bpermute_b32 v212, v194, v212
	v_cndmask_b32_e64 v188, v190, v188, s[14:15]
	v_cndmask_b32_e64 v189, v191, v189, s[14:15]
	v_cvt_scalef32_pk_bf16_fp8 v191, v38, 1.0
	s_waitcnt lgkmcnt(1)
	v_add_f32_e32 v188, v188, v211
	s_waitcnt lgkmcnt(0)
	v_add_f32_e32 v189, v189, v212
	v_cvt_scalef32_pk_bf16_fp8 v211, v38, 1.0 op_sel:[1,0,0]
	v_cvt_scalef32_pk_bf16_fp8 v212, v39, 1.0
	v_cvt_scalef32_pk_bf16_fp8 v213, v39, 1.0 op_sel:[1,0,0]
	v_cvt_scalef32_pk_bf16_fp8 v214, v40, 1.0
	v_cvt_scalef32_pk_bf16_fp8 v215, v40, 1.0 op_sel:[1,0,0]
	v_cvt_scalef32_pk_bf16_fp8 v217, v41, 1.0 op_sel:[1,0,0]
	v_cvt_scalef32_pk_bf16_fp8 v216, v41, 1.0
	v_dot2_f32_bf16 v218, v191, v66, 0
	v_dot2_f32_bf16 v218, v211, v67, v218
	v_dot2_f32_bf16 v218, v212, v68, v218
	v_dot2_f32_bf16 v218, v213, v69, v218
	v_dot2_f32_bf16 v218, v214, v70, v218
	v_dot2_f32_bf16 v218, v215, v71, v218
	v_dot2_f32_bf16 v218, v216, v72, v218
	v_dot2_f32_bf16 v218, v217, v73, v218
	v_cvt_scalef32_pk_bf16_fp8 v191, v34, 1.0
	v_cvt_scalef32_pk_bf16_fp8 v211, v34, 1.0 op_sel:[1,0,0]
	v_cvt_scalef32_pk_bf16_fp8 v212, v35, 1.0
	v_cvt_scalef32_pk_bf16_fp8 v213, v35, 1.0 op_sel:[1,0,0]
	v_cvt_scalef32_pk_bf16_fp8 v214, v36, 1.0
	v_cvt_scalef32_pk_bf16_fp8 v215, v36, 1.0 op_sel:[1,0,0]
	v_cvt_scalef32_pk_bf16_fp8 v217, v37, 1.0 op_sel:[1,0,0]
	v_cvt_scalef32_pk_bf16_fp8 v216, v37, 1.0
	v_dot2_f32_bf16 v219, v191, v66, 0
	v_dot2_f32_bf16 v219, v211, v67, v219
	v_dot2_f32_bf16 v219, v212, v68, v219
	v_dot2_f32_bf16 v219, v213, v69, v219
	v_dot2_f32_bf16 v219, v214, v70, v219
	v_dot2_f32_bf16 v219, v215, v71, v219
	v_dot2_f32_bf16 v219, v216, v72, v219
	v_dot2_f32_bf16 v219, v217, v73, v219
	v_cvt_scalef32_pk_bf16_fp8 v191, v46, 1.0
	v_cvt_scalef32_pk_bf16_fp8 v211, v46, 1.0 op_sel:[1,0,0]
	v_cvt_scalef32_pk_bf16_fp8 v212, v47, 1.0
	v_cvt_scalef32_pk_bf16_fp8 v213, v47, 1.0 op_sel:[1,0,0]
	v_cvt_scalef32_pk_bf16_fp8 v214, v48, 1.0
	v_cvt_scalef32_pk_bf16_fp8 v215, v48, 1.0 op_sel:[1,0,0]
	v_cvt_scalef32_pk_bf16_fp8 v217, v49, 1.0 op_sel:[1,0,0]
	v_cvt_scalef32_pk_bf16_fp8 v216, v49, 1.0
	v_dot2_f32_bf16 v220, v191, v66, 0
	v_dot2_f32_bf16 v220, v211, v67, v220
	v_dot2_f32_bf16 v220, v212, v68, v220
	v_dot2_f32_bf16 v220, v213, v69, v220
	v_dot2_f32_bf16 v220, v214, v70, v220
	v_dot2_f32_bf16 v220, v215, v71, v220
	v_dot2_f32_bf16 v220, v216, v72, v220
	v_dot2_f32_bf16 v220, v217, v73, v220
	v_cvt_scalef32_pk_bf16_fp8 v191, v42, 1.0
	v_cvt_scalef32_pk_bf16_fp8 v211, v42, 1.0 op_sel:[1,0,0]
	v_cvt_scalef32_pk_bf16_fp8 v212, v43, 1.0
	v_cvt_scalef32_pk_bf16_fp8 v213, v43, 1.0 op_sel:[1,0,0]
	v_cvt_scalef32_pk_bf16_fp8 v214, v44, 1.0
	v_cvt_scalef32_pk_bf16_fp8 v215, v44, 1.0 op_sel:[1,0,0]
	v_cvt_scalef32_pk_bf16_fp8 v217, v45, 1.0 op_sel:[1,0,0]
	v_cvt_scalef32_pk_bf16_fp8 v216, v45, 1.0
	v_dot2_f32_bf16 v221, v191, v66, 0
	v_dot2_f32_bf16 v221, v211, v67, v221
	v_dot2_f32_bf16 v221, v212, v68, v221
	v_dot2_f32_bf16 v221, v213, v69, v221
	v_dot2_f32_bf16 v221, v214, v70, v221
	v_dot2_f32_bf16 v221, v215, v71, v221
	v_dot2_f32_bf16 v221, v216, v72, v221
	v_dot2_f32_bf16 v221, v217, v73, v221
	v_cvt_scalef32_pk_bf16_fp8 v191, v54, 1.0
	v_cvt_scalef32_pk_bf16_fp8 v211, v54, 1.0 op_sel:[1,0,0]
	v_cvt_scalef32_pk_bf16_fp8 v212, v55, 1.0
	v_cvt_scalef32_pk_bf16_fp8 v213, v55, 1.0 op_sel:[1,0,0]
	v_cvt_scalef32_pk_bf16_fp8 v214, v56, 1.0
	v_cvt_scalef32_pk_bf16_fp8 v215, v56, 1.0 op_sel:[1,0,0]
	v_cvt_scalef32_pk_bf16_fp8 v217, v57, 1.0 op_sel:[1,0,0]
	v_cvt_scalef32_pk_bf16_fp8 v216, v57, 1.0
	v_dot2_f32_bf16 v222, v191, v66, 0
	v_dot2_f32_bf16 v222, v211, v67, v222
	v_dot2_f32_bf16 v222, v212, v68, v222
	v_dot2_f32_bf16 v222, v213, v69, v222
	v_dot2_f32_bf16 v222, v214, v70, v222
	v_dot2_f32_bf16 v222, v215, v71, v222
	v_dot2_f32_bf16 v222, v216, v72, v222
	v_dot2_f32_bf16 v222, v217, v73, v222
	v_cvt_scalef32_pk_bf16_fp8 v191, v50, 1.0
	v_cvt_scalef32_pk_bf16_fp8 v211, v50, 1.0 op_sel:[1,0,0]
	v_cvt_scalef32_pk_bf16_fp8 v212, v51, 1.0
	v_cvt_scalef32_pk_bf16_fp8 v213, v51, 1.0 op_sel:[1,0,0]
	v_cvt_scalef32_pk_bf16_fp8 v214, v52, 1.0
	v_cvt_scalef32_pk_bf16_fp8 v215, v52, 1.0 op_sel:[1,0,0]
	v_cvt_scalef32_pk_bf16_fp8 v217, v53, 1.0 op_sel:[1,0,0]
	v_cvt_scalef32_pk_bf16_fp8 v216, v53, 1.0
	v_dot2_f32_bf16 v223, v191, v66, 0
	v_dot2_f32_bf16 v223, v211, v67, v223
	v_dot2_f32_bf16 v223, v212, v68, v223
	v_dot2_f32_bf16 v223, v213, v69, v223
	v_dot2_f32_bf16 v223, v214, v70, v223
	v_dot2_f32_bf16 v223, v215, v71, v223
	v_dot2_f32_bf16 v223, v216, v72, v223
	v_dot2_f32_bf16 v223, v217, v73, v223
	v_cvt_scalef32_pk_bf16_fp8 v191, v62, 1.0
	v_cvt_scalef32_pk_bf16_fp8 v211, v62, 1.0 op_sel:[1,0,0]
	v_cvt_scalef32_pk_bf16_fp8 v212, v63, 1.0
	v_cvt_scalef32_pk_bf16_fp8 v213, v63, 1.0 op_sel:[1,0,0]
	v_cvt_scalef32_pk_bf16_fp8 v214, v64, 1.0
	v_cvt_scalef32_pk_bf16_fp8 v215, v64, 1.0 op_sel:[1,0,0]
	v_cvt_scalef32_pk_bf16_fp8 v217, v65, 1.0 op_sel:[1,0,0]
	v_cvt_scalef32_pk_bf16_fp8 v216, v65, 1.0
	v_dot2_f32_bf16 v224, v191, v66, 0
	v_dot2_f32_bf16 v224, v211, v67, v224
	v_dot2_f32_bf16 v224, v212, v68, v224
	v_dot2_f32_bf16 v224, v213, v69, v224
	v_dot2_f32_bf16 v224, v214, v70, v224
	v_dot2_f32_bf16 v224, v215, v71, v224
	v_dot2_f32_bf16 v224, v216, v72, v224
	v_dot2_f32_bf16 v224, v217, v73, v224
	v_cvt_scalef32_pk_bf16_fp8 v191, v58, 1.0
	v_cvt_scalef32_pk_bf16_fp8 v211, v58, 1.0 op_sel:[1,0,0]
	v_cvt_scalef32_pk_bf16_fp8 v212, v59, 1.0
	v_cvt_scalef32_pk_bf16_fp8 v213, v59, 1.0 op_sel:[1,0,0]
	v_cvt_scalef32_pk_bf16_fp8 v214, v60, 1.0
	v_cvt_scalef32_pk_bf16_fp8 v215, v60, 1.0 op_sel:[1,0,0]
	v_cvt_scalef32_pk_bf16_fp8 v217, v61, 1.0
	v_cvt_scalef32_pk_bf16_fp8 v225, v61, 1.0 op_sel:[1,0,0]
	v_dot2_f32_bf16 v226, v191, v66, 0
	v_dot2_f32_bf16 v226, v211, v67, v226
	v_dot2_f32_bf16 v226, v212, v68, v226
	v_dot2_f32_bf16 v226, v213, v69, v226
	v_dot2_f32_bf16 v226, v214, v70, v226
	v_dot2_f32_bf16 v226, v215, v71, v226
	v_dot2_f32_bf16 v226, v217, v72, v226
	v_dot2_f32_bf16 v226, v225, v73, v226
	v_cndmask_b32_e64 v68, v219, v223, s[12:13]
	ds_bpermute_b32 v68, v193, v68
	v_cndmask_b32_e64 v69, v220, v224, s[12:13]
	v_cndmask_b32_e64 v216, v218, v222, s[12:13]
	ds_bpermute_b32 v69, v193, v69
	v_cndmask_b32_e64 v70, v221, v226, s[12:13]
	ds_bpermute_b32 v216, v193, v216
	ds_bpermute_b32 v70, v193, v70
	v_cndmask_b32_e64 v67, v223, v219, s[12:13]
	s_waitcnt lgkmcnt(3)
; DI void peer_u_phase(const bf16_t* __restrict__ x1, const int* __restrict__ eidx, const unsigned char* __restrict__ U8, float* __restrict__ ph) {
;     ...
;                 xa = xan; xb = xbn;
	v_add_f32_e32 v67, v67, v68
	v_cndmask_b32_e64 v68, v224, v220, s[12:13]
	v_cndmask_b32_e64 v66, v222, v218, s[12:13]
	s_waitcnt lgkmcnt(2)
	v_add_f32_e32 v68, v68, v69
	v_cndmask_b32_e64 v69, v226, v221, s[12:13]
	s_waitcnt lgkmcnt(1)
	v_add_f32_e32 v66, v66, v216
	s_waitcnt lgkmcnt(0)
	v_add_f32_e32 v69, v69, v70
	v_cndmask_b32_e64 v70, v66, v68, s[14:15]
	v_cndmask_b32_e64 v71, v67, v69, s[14:15]
	ds_bpermute_b32 v70, v194, v70
	ds_bpermute_b32 v71, v194, v71
	v_cndmask_b32_e64 v66, v68, v66, s[14:15]
	v_cndmask_b32_e64 v67, v69, v67, s[14:15]
	v_cndmask_b32_e64 v190, v188, v189, s[16:17]
	s_waitcnt lgkmcnt(1)
	v_add_f32_e32 v66, v66, v70
	s_waitcnt lgkmcnt(0)
	v_add_f32_e32 v67, v67, v71
	v_cndmask_b32_e64 v68, v66, v67, s[16:17]
	ds_bpermute_b32 v72, v195, v190
	ds_bpermute_b32 v68, v195, v68
	v_cndmask_b32_e64 v69, v189, v188, s[16:17]
	v_cndmask_b32_e64 v66, v67, v66, s[16:17]
	s_waitcnt lgkmcnt(1)
	v_add_f32_e32 v69, v69, v72
	s_waitcnt lgkmcnt(0)
	v_add_f32_e32 v68, v66, v68
	s_setprio 0
	v_lshlrev_b64 v[66:67], 12, v[186:187]
	v_lshl_add_u64 v[66:67], v[184:185], 0, v[66:67]
	global_store_dword v[66:67], v69, off
	global_store_dword v[66:67], v68, off offset:256
	s_waitcnt vmcnt(2)
	v_mov_b64_e32 v[66:67], v[74:75]
	v_mov_b64_e32 v[70:71], v[142:143]
	v_mov_b64_e32 v[68:69], v[76:77]
	v_mov_b64_e32 v[72:73], v[144:145]

; DI float dot16(const unsigned (&a)[8], u32x4 b0, u32x4 b1) {
;     float acc;
;     asm volatile("v_dot2_f32_bf16 %0, %1, %9, 0\n\tv_dot2_f32_bf16 %0, %2, %10, %0\n\tv_dot2_f32_bf16 %0, %3, %11, %0\n\tv_dot2_f32_bf16 %0, %4, %12, %0\n\t"
;                  "v_dot2_f32_bf16 %0, %5, %13, %0\n\tv_dot2_f32_bf16 %0, %6, %14, %0\n\tv_dot2_f32_bf16 %0, %7, %15, %0\n\tv_dot2_f32_bf16 %0, %8, %16, %0\n\ts_nop 2"
;                  : "=&v"(acc)
;                  : "v"(a[0]), "v"(a[1]), "v"(a[2]), "v"(a[3]), "v"(a[4]), "v"(a[5]), "v"(a[6]), "v"(a[7]),
;                    "v"(b0.x), "v"(b0.y), "v"(b0.z), "v"(b0.w), "v"(b1.x), "v"(b1.y), "v"(b1.z), "v"(b1.w));
;     return acc;
; }
; DI float dot_fp8_row(u32x4 u, u32x4 xa, u32x4 xb) {
;     unsigned a[8];
; #pragma unroll
;     for (int j = 0; j < 4; ++j) {
;         a[2 * j] = __builtin_bit_cast(unsigned, __builtin_amdgcn_cvt_scalef32_pk_bf16_fp8(u[j], 1.0f, false));
;         a[2 * j + 1] = __builtin_bit_cast(unsigned, __builtin_amdgcn_cvt_scalef32_pk_bf16_fp8(u[j], 1.0f, true));
;     }
;     return dot16(a, xa, xb);
; }
.LBB0_535:
	s_or_b64 exec, exec, s[0:1]
	s_setprio 1
	s_waitcnt vmcnt(15)
	v_cvt_scalef32_pk_bf16_fp8 v213, v79, 1.0
	v_cvt_scalef32_pk_bf16_fp8 v189, v78, 1.0
	v_cvt_scalef32_pk_bf16_fp8 v212, v78, 1.0 op_sel:[1,0,0]
	v_cvt_scalef32_pk_bf16_fp8 v214, v79, 1.0 op_sel:[1,0,0]
	v_cvt_scalef32_pk_bf16_fp8 v215, v80, 1.0
	v_cvt_scalef32_pk_bf16_fp8 v216, v80, 1.0 op_sel:[1,0,0]
	v_cvt_scalef32_pk_bf16_fp8 v217, v81, 1.0
	v_cvt_scalef32_pk_bf16_fp8 v218, v81, 1.0 op_sel:[1,0,0]
	v_dot2_f32_bf16 v219, v189, v74, 0
	v_dot2_f32_bf16 v219, v212, v75, v219
	v_dot2_f32_bf16 v219, v213, v76, v219
	v_dot2_f32_bf16 v219, v214, v77, v219
	v_dot2_f32_bf16 v219, v215, v142, v219
	v_dot2_f32_bf16 v219, v216, v143, v219
	v_dot2_f32_bf16 v219, v217, v144, v219
	v_dot2_f32_bf16 v219, v218, v145, v219
	s_waitcnt vmcnt(14)
	v_cvt_scalef32_pk_bf16_fp8 v213, v83, 1.0
	v_cvt_scalef32_pk_bf16_fp8 v189, v82, 1.0
	v_cvt_scalef32_pk_bf16_fp8 v212, v82, 1.0 op_sel:[1,0,0]
	v_cvt_scalef32_pk_bf16_fp8 v214, v83, 1.0 op_sel:[1,0,0]
	v_cvt_scalef32_pk_bf16_fp8 v215, v84, 1.0
	v_cvt_scalef32_pk_bf16_fp8 v216, v84, 1.0 op_sel:[1,0,0]
	v_cvt_scalef32_pk_bf16_fp8 v217, v85, 1.0
	v_cvt_scalef32_pk_bf16_fp8 v218, v85, 1.0 op_sel:[1,0,0]
	v_dot2_f32_bf16 v220, v189, v74, 0
	v_dot2_f32_bf16 v220, v212, v75, v220
	v_dot2_f32_bf16 v220, v213, v76, v220
	v_dot2_f32_bf16 v220, v214, v77, v220
	v_dot2_f32_bf16 v220, v215, v142, v220
	v_dot2_f32_bf16 v220, v216, v143, v220
	v_dot2_f32_bf16 v220, v217, v144, v220
	v_dot2_f32_bf16 v220, v218, v145, v220
	s_waitcnt vmcnt(13)
	v_cvt_scalef32_pk_bf16_fp8 v213, v87, 1.0
	v_cvt_scalef32_pk_bf16_fp8 v189, v86, 1.0
	v_cvt_scalef32_pk_bf16_fp8 v212, v86, 1.0 op_sel:[1,0,0]
	v_cvt_scalef32_pk_bf16_fp8 v214, v87, 1.0 op_sel:[1,0,0]
	v_cvt_scalef32_pk_bf16_fp8 v215, v88, 1.0
	v_cvt_scalef32_pk_bf16_fp8 v216, v88, 1.0 op_sel:[1,0,0]
	v_cvt_scalef32_pk_bf16_fp8 v217, v89, 1.0
	v_cvt_scalef32_pk_bf16_fp8 v218, v89, 1.0 op_sel:[1,0,0]
	v_dot2_f32_bf16 v221, v189, v74, 0
	v_dot2_f32_bf16 v221, v212, v75, v221
	v_dot2_f32_bf16 v221, v213, v76, v221
	v_dot2_f32_bf16 v221, v214, v77, v221
	v_dot2_f32_bf16 v221, v215, v142, v221
	v_dot2_f32_bf16 v221, v216, v143, v221
	v_dot2_f32_bf16 v221, v217, v144, v221
	v_dot2_f32_bf16 v221, v218, v145, v221
	s_waitcnt vmcnt(12)
	v_cvt_scalef32_pk_bf16_fp8 v213, v91, 1.0
	v_cvt_scalef32_pk_bf16_fp8 v189, v90, 1.0
	v_cvt_scalef32_pk_bf16_fp8 v212, v90, 1.0 op_sel:[1,0,0]
	v_cvt_scalef32_pk_bf16_fp8 v214, v91, 1.0 op_sel:[1,0,0]
	v_cvt_scalef32_pk_bf16_fp8 v215, v92, 1.0
	v_cvt_scalef32_pk_bf16_fp8 v216, v92, 1.0 op_sel:[1,0,0]
	v_cvt_scalef32_pk_bf16_fp8 v217, v93, 1.0
	v_cvt_scalef32_pk_bf16_fp8 v218, v93, 1.0 op_sel:[1,0,0]
	v_dot2_f32_bf16 v222, v189, v74, 0
	v_dot2_f32_bf16 v222, v212, v75, v222
	v_dot2_f32_bf16 v222, v213, v76, v222
	v_dot2_f32_bf16 v222, v214, v77, v222
	v_dot2_f32_bf16 v222, v215, v142, v222
	v_dot2_f32_bf16 v222, v216, v143, v222
	v_dot2_f32_bf16 v222, v217, v144, v222
	v_dot2_f32_bf16 v222, v218, v145, v222
	s_waitcnt vmcnt(11)
	v_cvt_scalef32_pk_bf16_fp8 v213, v95, 1.0
	v_cvt_scalef32_pk_bf16_fp8 v189, v94, 1.0
	v_cvt_scalef32_pk_bf16_fp8 v212, v94, 1.0 op_sel:[1,0,0]
	v_cvt_scalef32_pk_bf16_fp8 v214, v95, 1.0 op_sel:[1,0,0]
	v_cvt_scalef32_pk_bf16_fp8 v215, v96, 1.0
	v_cvt_scalef32_pk_bf16_fp8 v216, v96, 1.0 op_sel:[1,0,0]
	v_cvt_scalef32_pk_bf16_fp8 v217, v97, 1.0
	v_cvt_scalef32_pk_bf16_fp8 v218, v97, 1.0 op_sel:[1,0,0]
	v_dot2_f32_bf16 v223, v189, v74, 0
	v_dot2_f32_bf16 v223, v212, v75, v223
	v_dot2_f32_bf16 v223, v213, v76, v223
	v_dot2_f32_bf16 v223, v214, v77, v223
	v_dot2_f32_bf16 v223, v215, v142, v223
	v_dot2_f32_bf16 v223, v216, v143, v223
	v_dot2_f32_bf16 v223, v217, v144, v223
	v_dot2_f32_bf16 v223, v218, v145, v223
	s_waitcnt vmcnt(10)
	v_cvt_scalef32_pk_bf16_fp8 v213, v99, 1.0
	v_cvt_scalef32_pk_bf16_fp8 v189, v98, 1.0
	v_cvt_scalef32_pk_bf16_fp8 v212, v98, 1.0 op_sel:[1,0,0]
	v_cvt_scalef32_pk_bf16_fp8 v214, v99, 1.0 op_sel:[1,0,0]
	v_cvt_scalef32_pk_bf16_fp8 v215, v100, 1.0
	v_cvt_scalef32_pk_bf16_fp8 v216, v100, 1.0 op_sel:[1,0,0]
	v_cvt_scalef32_pk_bf16_fp8 v217, v101, 1.0
	v_cvt_scalef32_pk_bf16_fp8 v218, v101, 1.0 op_sel:[1,0,0]
	v_dot2_f32_bf16 v224, v189, v74, 0
	v_dot2_f32_bf16 v224, v212, v75, v224
	v_dot2_f32_bf16 v224, v213, v76, v224
	v_dot2_f32_bf16 v224, v214, v77, v224
	v_dot2_f32_bf16 v224, v215, v142, v224
	v_dot2_f32_bf16 v224, v216, v143, v224
	v_dot2_f32_bf16 v224, v217, v144, v224
	v_dot2_f32_bf16 v224, v218, v145, v224
	s_waitcnt vmcnt(9)
	v_cvt_scalef32_pk_bf16_fp8 v213, v103, 1.0
	v_cvt_scalef32_pk_bf16_fp8 v189, v102, 1.0
	v_cvt_scalef32_pk_bf16_fp8 v212, v102, 1.0 op_sel:[1,0,0]
	v_cvt_scalef32_pk_bf16_fp8 v214, v103, 1.0 op_sel:[1,0,0]
	v_cvt_scalef32_pk_bf16_fp8 v215, v104, 1.0
	v_cvt_scalef32_pk_bf16_fp8 v216, v104, 1.0 op_sel:[1,0,0]
	v_cvt_scalef32_pk_bf16_fp8 v217, v105, 1.0
	v_cvt_scalef32_pk_bf16_fp8 v218, v105, 1.0 op_sel:[1,0,0]
	v_dot2_f32_bf16 v225, v189, v74, 0
	v_dot2_f32_bf16 v225, v212, v75, v225
	v_dot2_f32_bf16 v225, v213, v76, v225
	v_dot2_f32_bf16 v225, v214, v77, v225
	v_dot2_f32_bf16 v225, v215, v142, v225
	v_dot2_f32_bf16 v225, v216, v143, v225
	v_dot2_f32_bf16 v225, v217, v144, v225
	v_dot2_f32_bf16 v225, v218, v145, v225
	s_waitcnt vmcnt(8)
; DI float dot16(const unsigned (&a)[8], u32x4 b0, u32x4 b1) {
;     float acc;
;     asm volatile("v_dot2_f32_bf16 %0, %1, %9, 0\n\tv_dot2_f32_bf16 %0, %2, %10, %0\n\tv_dot2_f32_bf16 %0, %3, %11, %0\n\tv_dot2_f32_bf16 %0, %4, %12, %0\n\t"
;                  "v_dot2_f32_bf16 %0, %5, %13, %0\n\tv_dot2_f32_bf16 %0, %6, %14, %0\n\tv_dot2_f32_bf16 %0, %7, %15, %0\n\tv_dot2_f32_bf16 %0, %8, %16, %0\n\ts_nop 2"
;                  : "=&v"(acc)
;                  : "v"(a[0]), "v"(a[1]), "v"(a[2]), "v"(a[3]), "v"(a[4]), "v"(a[5]), "v"(a[6]), "v"(a[7]),
;                    "v"(b0.x), "v"(b0.y), "v"(b0.z), "v"(b0.w), "v"(b1.x), "v"(b1.y), "v"(b1.z), "v"(b1.w));
;     return acc;
; }
; DI float dot_fp8_row(u32x4 u, u32x4 xa, u32x4 xb) {
;     unsigned a[8];
; #pragma unroll
;     for (int j = 0; j < 4; ++j) {
;         a[2 * j] = __builtin_bit_cast(unsigned, __builtin_amdgcn_cvt_scalef32_pk_bf16_fp8(u[j], 1.0f, false));
;         a[2 * j + 1] = __builtin_bit_cast(unsigned, __builtin_amdgcn_cvt_scalef32_pk_bf16_fp8(u[j], 1.0f, true));
;     }
;     return dot16(a, xa, xb);
; }
	v_cvt_scalef32_pk_bf16_fp8 v213, v107, 1.0
	v_cvt_scalef32_pk_bf16_fp8 v189, v106, 1.0
	v_cvt_scalef32_pk_bf16_fp8 v212, v106, 1.0 op_sel:[1,0,0]
	v_cvt_scalef32_pk_bf16_fp8 v214, v107, 1.0 op_sel:[1,0,0]
	v_cvt_scalef32_pk_bf16_fp8 v215, v108, 1.0
	v_cvt_scalef32_pk_bf16_fp8 v216, v108, 1.0 op_sel:[1,0,0]
	v_cvt_scalef32_pk_bf16_fp8 v218, v109, 1.0
	v_cvt_scalef32_pk_bf16_fp8 v226, v109, 1.0 op_sel:[1,0,0]
	v_dot2_f32_bf16 v227, v189, v74, 0
	v_dot2_f32_bf16 v227, v212, v75, v227
	v_dot2_f32_bf16 v227, v213, v76, v227
	v_dot2_f32_bf16 v227, v214, v77, v227
	v_dot2_f32_bf16 v227, v215, v142, v227
	v_dot2_f32_bf16 v227, v216, v143, v227
	v_dot2_f32_bf16 v227, v218, v144, v227
	v_dot2_f32_bf16 v227, v226, v145, v227
	v_cndmask_b32_e64 v213, v220, v224, s[12:13]
	ds_bpermute_b32 v213, v193, v213
	v_cndmask_b32_e64 v214, v221, v225, s[12:13]
	ds_bpermute_b32 v214, v193, v214
	v_cndmask_b32_e64 v215, v222, v227, s[12:13]
	v_cndmask_b32_e64 v217, v219, v223, s[12:13]
	ds_bpermute_b32 v215, v193, v215
	ds_bpermute_b32 v217, v193, v217
	v_cndmask_b32_e64 v212, v224, v220, s[12:13]
	s_waitcnt lgkmcnt(3)
	v_add_f32_e32 v212, v212, v213
	v_cndmask_b32_e64 v213, v225, v221, s[12:13]
	s_waitcnt lgkmcnt(2)
	v_add_f32_e32 v213, v213, v214
	v_cndmask_b32_e64 v214, v227, v222, s[12:13]
	v_cndmask_b32_e64 v189, v223, v219, s[12:13]
	s_waitcnt lgkmcnt(1)
	v_add_f32_e32 v214, v214, v215
	s_waitcnt lgkmcnt(0)
	v_add_f32_e32 v189, v189, v217
	v_cndmask_b32_e64 v216, v212, v214, s[14:15]
	v_cndmask_b32_e64 v215, v189, v213, s[14:15]
	ds_bpermute_b32 v216, v194, v216
	ds_bpermute_b32 v215, v194, v215
	v_cndmask_b32_e64 v212, v214, v212, s[14:15]
	v_cndmask_b32_e64 v189, v213, v189, s[14:15]
	s_waitcnt vmcnt(7)
	v_cvt_scalef32_pk_bf16_fp8 v214, v110, 1.0
	s_waitcnt lgkmcnt(1)
	v_add_f32_e32 v212, v212, v216
	v_cvt_scalef32_pk_bf16_fp8 v216, v111, 1.0
	s_waitcnt lgkmcnt(0)
	v_add_f32_e32 v189, v189, v215
	v_cvt_scalef32_pk_bf16_fp8 v215, v110, 1.0 op_sel:[1,0,0]
	v_cvt_scalef32_pk_bf16_fp8 v217, v111, 1.0 op_sel:[1,0,0]
	v_cvt_scalef32_pk_bf16_fp8 v218, v112, 1.0
	v_cvt_scalef32_pk_bf16_fp8 v219, v112, 1.0 op_sel:[1,0,0]
	v_cvt_scalef32_pk_bf16_fp8 v220, v113, 1.0
	v_cvt_scalef32_pk_bf16_fp8 v221, v113, 1.0 op_sel:[1,0,0]
	v_dot2_f32_bf16 v222, v214, v74, 0
	v_dot2_f32_bf16 v222, v215, v75, v222
	v_dot2_f32_bf16 v222, v216, v76, v222
	v_dot2_f32_bf16 v222, v217, v77, v222
	v_dot2_f32_bf16 v222, v218, v142, v222
	v_dot2_f32_bf16 v222, v219, v143, v222
	v_dot2_f32_bf16 v222, v220, v144, v222
	v_dot2_f32_bf16 v222, v221, v145, v222
	s_waitcnt vmcnt(6)
	v_cvt_scalef32_pk_bf16_fp8 v216, v115, 1.0
	v_cvt_scalef32_pk_bf16_fp8 v214, v114, 1.0
	v_cvt_scalef32_pk_bf16_fp8 v215, v114, 1.0 op_sel:[1,0,0]
	v_cvt_scalef32_pk_bf16_fp8 v217, v115, 1.0 op_sel:[1,0,0]
	v_cvt_scalef32_pk_bf16_fp8 v218, v116, 1.0
	v_cvt_scalef32_pk_bf16_fp8 v219, v116, 1.0 op_sel:[1,0,0]
	v_cvt_scalef32_pk_bf16_fp8 v220, v117, 1.0
	v_cvt_scalef32_pk_bf16_fp8 v221, v117, 1.0 op_sel:[1,0,0]
	v_dot2_f32_bf16 v223, v214, v74, 0
	v_dot2_f32_bf16 v223, v215, v75, v223
	v_dot2_f32_bf16 v223, v216, v76, v223
	v_dot2_f32_bf16 v223, v217, v77, v223
	v_dot2_f32_bf16 v223, v218, v142, v223
	v_dot2_f32_bf16 v223, v219, v143, v223
	v_dot2_f32_bf16 v223, v220, v144, v223
	v_dot2_f32_bf16 v223, v221, v145, v223
	s_waitcnt vmcnt(5)
	v_cvt_scalef32_pk_bf16_fp8 v216, v119, 1.0
	v_cvt_scalef32_pk_bf16_fp8 v214, v118, 1.0
	v_cvt_scalef32_pk_bf16_fp8 v215, v118, 1.0 op_sel:[1,0,0]
	v_cvt_scalef32_pk_bf16_fp8 v217, v119, 1.0 op_sel:[1,0,0]
	v_cvt_scalef32_pk_bf16_fp8 v218, v120, 1.0
	v_cvt_scalef32_pk_bf16_fp8 v219, v120, 1.0 op_sel:[1,0,0]
	v_cvt_scalef32_pk_bf16_fp8 v220, v121, 1.0
	v_cvt_scalef32_pk_bf16_fp8 v221, v121, 1.0 op_sel:[1,0,0]
	v_dot2_f32_bf16 v224, v214, v74, 0
	v_dot2_f32_bf16 v224, v215, v75, v224
	v_dot2_f32_bf16 v224, v216, v76, v224
	v_dot2_f32_bf16 v224, v217, v77, v224
	v_dot2_f32_bf16 v224, v218, v142, v224
	v_dot2_f32_bf16 v224, v219, v143, v224
	v_dot2_f32_bf16 v224, v220, v144, v224
	v_dot2_f32_bf16 v224, v221, v145, v224
	s_waitcnt vmcnt(4)
	v_cvt_scalef32_pk_bf16_fp8 v216, v123, 1.0
	v_cvt_scalef32_pk_bf16_fp8 v214, v122, 1.0
	v_cvt_scalef32_pk_bf16_fp8 v215, v122, 1.0 op_sel:[1,0,0]
	v_cvt_scalef32_pk_bf16_fp8 v217, v123, 1.0 op_sel:[1,0,0]
	v_cvt_scalef32_pk_bf16_fp8 v218, v124, 1.0
	v_cvt_scalef32_pk_bf16_fp8 v219, v124, 1.0 op_sel:[1,0,0]
	v_cvt_scalef32_pk_bf16_fp8 v220, v125, 1.0
	v_cvt_scalef32_pk_bf16_fp8 v221, v125, 1.0 op_sel:[1,0,0]
	v_dot2_f32_bf16 v225, v214, v74, 0
	v_dot2_f32_bf16 v225, v215, v75, v225
	v_dot2_f32_bf16 v225, v216, v76, v225
	v_dot2_f32_bf16 v225, v217, v77, v225
	v_dot2_f32_bf16 v225, v218, v142, v225
	v_dot2_f32_bf16 v225, v219, v143, v225
	v_dot2_f32_bf16 v225, v220, v144, v225
	v_dot2_f32_bf16 v225, v221, v145, v225
	s_waitcnt vmcnt(3)
	v_cvt_scalef32_pk_bf16_fp8 v216, v127, 1.0
	v_cvt_scalef32_pk_bf16_fp8 v214, v126, 1.0
	v_cvt_scalef32_pk_bf16_fp8 v215, v126, 1.0 op_sel:[1,0,0]
	v_cvt_scalef32_pk_bf16_fp8 v217, v127, 1.0 op_sel:[1,0,0]
	v_cvt_scalef32_pk_bf16_fp8 v218, v128, 1.0
	v_cvt_scalef32_pk_bf16_fp8 v219, v128, 1.0 op_sel:[1,0,0]
	v_cvt_scalef32_pk_bf16_fp8 v220, v129, 1.0
	v_cvt_scalef32_pk_bf16_fp8 v221, v129, 1.0 op_sel:[1,0,0]
	v_dot2_f32_bf16 v226, v214, v74, 0
	v_dot2_f32_bf16 v226, v215, v75, v226
	v_dot2_f32_bf16 v226, v216, v76, v226
	v_dot2_f32_bf16 v226, v217, v77, v226
	v_dot2_f32_bf16 v226, v218, v142, v226
	v_dot2_f32_bf16 v226, v219, v143, v226
	v_dot2_f32_bf16 v226, v220, v144, v226
	v_dot2_f32_bf16 v226, v221, v145, v226
	s_waitcnt vmcnt(2)
; #define U_ISSUE(SEG, E0, E1) { _Pragma("unroll") for (int b = 0; b < 16; ++b) { const int e = __shfl((b < 8) ? (E0) : (E1), (b & 7) * 8 + grp); SEG[b] = *(const u32x4*)(ub + (size_t)e * DM); } }
; DI void peer_u_phase(const bf16_t* __restrict__ x1, const int* __restrict__ eidx, const unsigned char* __restrict__ U8, float* __restrict__ ph) {
;     ...
;         {
;             const int e0 = eidx[(size_t)t * 128 + lane], e1 = eidx[(size_t)t * 128 + 64 + lane];
;             xa = *(const u32x4*)(xb_ + (size_t)t * DM); xb = *(const u32x4*)(xb_ + (size_t)t * DM + 8);
;             U_ISSUE(sa, e0, e1)
;             if (t + step < T_TOK) { e0n = eidx[(size_t)(t + step) * 128 + lane]; e1n = eidx[(size_t)(t + step) * 128 + 64 + lane]; }
;         }
;         for (; t < T_TOK; t += 2 * step) {
;             int e0nn = 0, e1nn = 0;
;             const bool n1 = t + step < T_TOK, n2 = t + 2 * step < T_TOK, n3 = t + 3 * step < T_TOK;
;             if (n1) { U_ISSUE(sb, e0n, e1n) xan = *(const u32x4*)(xb_ + (size_t)(t + step) * DM); xbn = *(const u32x4*)(xb_ + (size_t)(t + step) * DM + 8); }
;             if (n2) { e0nn = eidx[(size_t)(t + 2 * step) * 128 + lane]; e1nn = eidx[(size_t)(t + 2 * step) * 128 + 64 + lane]; }
;             U_COMPUTE(sa, t)
;             if (n1) {
;                 xa = xan; xb = xbn;
;                 if (n2) { U_ISSUE(sa, e0nn, e1nn) xan = *(const u32x4*)(xb_ + (size_t)(t + 2 * step) * DM); xbn = *(const u32x4*)(xb_ + (size_t)(t + 2 * step) * DM + 8); }
	v_cvt_scalef32_pk_bf16_fp8 v216, v131, 1.0
	v_cvt_scalef32_pk_bf16_fp8 v214, v130, 1.0
	v_cvt_scalef32_pk_bf16_fp8 v215, v130, 1.0 op_sel:[1,0,0]
	v_cvt_scalef32_pk_bf16_fp8 v217, v131, 1.0 op_sel:[1,0,0]
	v_cvt_scalef32_pk_bf16_fp8 v218, v132, 1.0
	v_cvt_scalef32_pk_bf16_fp8 v219, v132, 1.0 op_sel:[1,0,0]
	v_cvt_scalef32_pk_bf16_fp8 v220, v133, 1.0
	v_cvt_scalef32_pk_bf16_fp8 v221, v133, 1.0 op_sel:[1,0,0]
	v_dot2_f32_bf16 v227, v214, v74, 0
	v_dot2_f32_bf16 v227, v215, v75, v227
	v_dot2_f32_bf16 v227, v216, v76, v227
	v_dot2_f32_bf16 v227, v217, v77, v227
	v_dot2_f32_bf16 v227, v218, v142, v227
	v_dot2_f32_bf16 v227, v219, v143, v227
	v_dot2_f32_bf16 v227, v220, v144, v227
	v_dot2_f32_bf16 v227, v221, v145, v227
	s_waitcnt vmcnt(1)
	v_cvt_scalef32_pk_bf16_fp8 v216, v135, 1.0
	v_cvt_scalef32_pk_bf16_fp8 v214, v134, 1.0
	v_cvt_scalef32_pk_bf16_fp8 v215, v134, 1.0 op_sel:[1,0,0]
	v_cvt_scalef32_pk_bf16_fp8 v217, v135, 1.0 op_sel:[1,0,0]
	v_cvt_scalef32_pk_bf16_fp8 v218, v136, 1.0
	v_cvt_scalef32_pk_bf16_fp8 v219, v136, 1.0 op_sel:[1,0,0]
	v_cvt_scalef32_pk_bf16_fp8 v220, v137, 1.0
	v_cvt_scalef32_pk_bf16_fp8 v221, v137, 1.0 op_sel:[1,0,0]
	v_dot2_f32_bf16 v228, v214, v74, 0
	v_dot2_f32_bf16 v228, v215, v75, v228
	v_dot2_f32_bf16 v228, v216, v76, v228
	v_dot2_f32_bf16 v228, v217, v77, v228
	v_dot2_f32_bf16 v228, v218, v142, v228
	v_dot2_f32_bf16 v228, v219, v143, v228
	v_dot2_f32_bf16 v228, v220, v144, v228
	v_dot2_f32_bf16 v228, v221, v145, v228
	s_waitcnt vmcnt(0)
	v_cvt_scalef32_pk_bf16_fp8 v216, v139, 1.0
	v_cvt_scalef32_pk_bf16_fp8 v214, v138, 1.0
	v_cvt_scalef32_pk_bf16_fp8 v215, v138, 1.0 op_sel:[1,0,0]
	v_cvt_scalef32_pk_bf16_fp8 v217, v139, 1.0 op_sel:[1,0,0]
	v_cvt_scalef32_pk_bf16_fp8 v218, v140, 1.0
	v_cvt_scalef32_pk_bf16_fp8 v219, v140, 1.0 op_sel:[1,0,0]
	v_cvt_scalef32_pk_bf16_fp8 v221, v141, 1.0
	v_cvt_scalef32_pk_bf16_fp8 v229, v141, 1.0 op_sel:[1,0,0]
	v_dot2_f32_bf16 v230, v214, v74, 0
	v_dot2_f32_bf16 v230, v215, v75, v230
	v_dot2_f32_bf16 v230, v216, v76, v230
	v_dot2_f32_bf16 v230, v217, v77, v230
	v_dot2_f32_bf16 v230, v218, v142, v230
	v_dot2_f32_bf16 v230, v219, v143, v230
	v_dot2_f32_bf16 v230, v221, v144, v230
	v_dot2_f32_bf16 v230, v229, v145, v230
	v_cndmask_b32_e64 v216, v223, v227, s[12:13]
	ds_bpermute_b32 v216, v193, v216
	v_cndmask_b32_e64 v217, v224, v228, s[12:13]
	v_cndmask_b32_e64 v220, v222, v226, s[12:13]
	ds_bpermute_b32 v217, v193, v217
	v_cndmask_b32_e64 v218, v225, v230, s[12:13]
	ds_bpermute_b32 v220, v193, v220
	ds_bpermute_b32 v218, v193, v218
	v_cndmask_b32_e64 v215, v227, v223, s[12:13]
	s_waitcnt lgkmcnt(3)
	v_add_f32_e32 v215, v215, v216
	v_cndmask_b32_e64 v216, v228, v224, s[12:13]
	v_cndmask_b32_e64 v214, v226, v222, s[12:13]
	s_waitcnt lgkmcnt(2)
	v_add_f32_e32 v216, v216, v217
	v_cndmask_b32_e64 v217, v230, v225, s[12:13]
	s_waitcnt lgkmcnt(1)
	v_add_f32_e32 v214, v214, v220
	s_waitcnt lgkmcnt(0)
	v_add_f32_e32 v217, v217, v218
	v_cndmask_b32_e64 v218, v214, v216, s[14:15]
	v_cndmask_b32_e64 v219, v215, v217, s[14:15]
	ds_bpermute_b32 v218, v194, v218
	ds_bpermute_b32 v219, v194, v219
	v_cndmask_b32_e64 v214, v216, v214, s[14:15]
	v_cndmask_b32_e64 v215, v217, v215, s[14:15]
	v_cndmask_b32_e64 v213, v189, v212, s[16:17]
	s_waitcnt lgkmcnt(1)
	v_add_f32_e32 v214, v214, v218
	s_waitcnt lgkmcnt(0)
	v_add_f32_e32 v215, v215, v219
	ds_bpermute_b32 v213, v195, v213
	v_cndmask_b32_e64 v216, v214, v215, s[16:17]
	ds_bpermute_b32 v216, v195, v216
	v_cndmask_b32_e64 v189, v212, v189, s[16:17]
	s_waitcnt lgkmcnt(1)
	v_add_f32_e32 v217, v189, v213
	v_cndmask_b32_e64 v189, v215, v214, s[16:17]
	s_waitcnt lgkmcnt(0)
	v_add_f32_e32 v214, v189, v216
	s_setprio 0
	v_ashrrev_i32_e32 v189, 31, v188
	v_lshlrev_b64 v[212:213], 12, v[188:189]
	v_lshl_add_u64 v[212:213], v[184:185], 0, v[212:213]
	global_store_dword v[212:213], v217, off
	global_store_dword v[212:213], v214, off offset:256
	s_and_saveexec_b64 s[74:75], s[18:19]
	s_cbranch_execz .LBB0_530
	v_mov_b64_e32 v[144:145], v[72:73]
	v_mov_b64_e32 v[76:77], v[68:69]
	v_mov_b64_e32 v[142:143], v[70:71]
	v_mov_b64_e32 v[74:75], v[66:67]
	s_and_saveexec_b64 s[0:1], s[20:21]
	s_cbranch_execz .LBB0_538
	ds_bpermute_b32 v74, v1, v211
	ds_bpermute_b32 v76, v149, v211
	ds_bpermute_b32 v86, v153, v211
	ds_bpermute_b32 v88, v198, v211
	ds_bpermute_b32 v94, v199, v211
	s_waitcnt lgkmcnt(4)
	ds_bpermute_b32 v96, v200, v211
	s_waitcnt lgkmcnt(4)
	v_lshl_add_u32 v74, v74, 7, v252
	ds_bpermute_b32 v102, v201, v211
	v_lshl_add_u32 v76, v76, 7, v252
	s_waitcnt lgkmcnt(4)
	ds_bpermute_b32 v104, v202, v211
	global_load_dwordx4 v[78:81], v74, s[98:99]
	global_load_dwordx4 v[82:85], v76, s[98:99]
	v_lshl_add_u32 v74, v86, 7, v252
	s_waitcnt lgkmcnt(4)
	ds_bpermute_b32 v110, v1, v191
	v_lshl_add_u32 v76, v88, 7, v252
	s_waitcnt lgkmcnt(4)
	ds_bpermute_b32 v112, v149, v191
	global_load_dwordx4 v[86:89], v74, s[98:99]
	global_load_dwordx4 v[90:93], v76, s[98:99]
	v_lshl_add_u32 v74, v94, 7, v252
	s_waitcnt lgkmcnt(4)
	ds_bpermute_b32 v118, v153, v191
	v_lshl_add_u32 v76, v96, 7, v252
	s_waitcnt lgkmcnt(4)
	ds_bpermute_b32 v120, v198, v191
	global_load_dwordx4 v[94:97], v74, s[98:99]
	global_load_dwordx4 v[98:101], v76, s[98:99]
	v_lshl_add_u32 v74, v102, 7, v252
	s_waitcnt lgkmcnt(4)
	ds_bpermute_b32 v126, v199, v191
	v_lshl_add_u32 v76, v104, 7, v252
	s_waitcnt lgkmcnt(4)
	ds_bpermute_b32 v128, v200, v191
	global_load_dwordx4 v[102:105], v74, s[98:99]
	global_load_dwordx4 v[106:109], v76, s[98:99]
	v_lshl_add_u32 v74, v110, 7, v252
	s_waitcnt lgkmcnt(4)
	ds_bpermute_b32 v134, v201, v191
	v_lshl_add_u32 v76, v112, 7, v252
	s_waitcnt lgkmcnt(4)
	ds_bpermute_b32 v136, v202, v191
	global_load_dwordx4 v[110:113], v74, s[98:99]
	global_load_dwordx4 v[114:117], v76, s[98:99]
	v_lshl_add_u32 v74, v118, 7, v252
	s_waitcnt lgkmcnt(4)
	v_lshl_add_u32 v76, v120, 7, v252
	s_waitcnt lgkmcnt(3)
	global_load_dwordx4 v[118:121], v74, s[98:99]
	global_load_dwordx4 v[122:125], v76, s[98:99]
	v_lshl_add_u32 v74, v126, 7, v252
	s_waitcnt lgkmcnt(2)
	v_lshl_add_u32 v76, v128, 7, v252
	s_waitcnt lgkmcnt(1)
	global_load_dwordx4 v[126:129], v74, s[98:99]
	global_load_dwordx4 v[130:133], v76, s[98:99]
	v_lshl_add_u32 v74, v134, 7, v252
	s_waitcnt lgkmcnt(0)
	v_lshl_add_u32 v76, v136, 7, v252
	v_ashrrev_i32_e32 v191, 31, v190
	global_load_dwordx4 v[134:137], v74, s[98:99]
	global_load_dwordx4 v[138:141], v76, s[98:99]
	v_lshlrev_b64 v[74:75], 11, v[190:191]
	v_lshl_add_u64 v[74:75], v[182:183], 0, v[74:75]
	global_load_dwordx4 v[142:145], v[74:75], off offset:16
	s_nop 0
	global_load_dwordx4 v[74:77], v[74:75], off

; DI float dot16(const unsigned (&a)[8], u32x4 b0, u32x4 b1) {
;     float acc;
;     asm volatile("v_dot2_f32_bf16 %0, %1, %9, 0\n\tv_dot2_f32_bf16 %0, %2, %10, %0\n\tv_dot2_f32_bf16 %0, %3, %11, %0\n\tv_dot2_f32_bf16 %0, %4, %12, %0\n\t"
;                  "v_dot2_f32_bf16 %0, %5, %13, %0\n\tv_dot2_f32_bf16 %0, %6, %14, %0\n\tv_dot2_f32_bf16 %0, %7, %15, %0\n\tv_dot2_f32_bf16 %0, %8, %16, %0\n\ts_nop 2"
;                  : "=&v"(acc)
;                  : "v"(a[0]), "v"(a[1]), "v"(a[2]), "v"(a[3]), "v"(a[4]), "v"(a[5]), "v"(a[6]), "v"(a[7]),
;                    "v"(b0.x), "v"(b0.y), "v"(b0.z), "v"(b0.w), "v"(b1.x), "v"(b1.y), "v"(b1.z), "v"(b1.w));
;     return acc;
; }
; DI float dot_fp8_row(u32x4 u, u32x4 xa, u32x4 xb) {
;     unsigned a[8];
; #pragma unroll
;     for (int j = 0; j < 4; ++j) {
;         a[2 * j] = __builtin_bit_cast(unsigned, __builtin_amdgcn_cvt_scalef32_pk_bf16_fp8(u[j], 1.0f, false));
;         a[2 * j + 1] = __builtin_bit_cast(unsigned, __builtin_amdgcn_cvt_scalef32_pk_bf16_fp8(u[j], 1.0f, true));
;     }
;     return dot16(a, xa, xb);
; }
.LBB0_1227:
	s_or_b64 exec, exec, s[14:15]
	s_setprio 1
	v_cvt_scalef32_pk_bf16_fp8 v184, v5, 1.0
	v_cvt_scalef32_pk_bf16_fp8 v182, v4, 1.0
	v_cvt_scalef32_pk_bf16_fp8 v183, v4, 1.0 op_sel:[1,0,0]
	v_cvt_scalef32_pk_bf16_fp8 v185, v5, 1.0 op_sel:[1,0,0]
	v_cvt_scalef32_pk_bf16_fp8 v201, v6, 1.0
	v_cvt_scalef32_pk_bf16_fp8 v202, v6, 1.0 op_sel:[1,0,0]
	v_cvt_scalef32_pk_bf16_fp8 v203, v7, 1.0
	v_cvt_scalef32_pk_bf16_fp8 v204, v7, 1.0 op_sel:[1,0,0]
	v_dot2_f32_bf16 v205, v182, v64, 0
	v_dot2_f32_bf16 v205, v183, v65, v205
	v_dot2_f32_bf16 v205, v184, v66, v205
	v_dot2_f32_bf16 v205, v185, v67, v205
	v_dot2_f32_bf16 v205, v201, v68, v205
	v_dot2_f32_bf16 v205, v202, v69, v205
	v_dot2_f32_bf16 v205, v203, v70, v205
	v_dot2_f32_bf16 v205, v204, v71, v205
	v_cvt_scalef32_pk_bf16_fp8 v184, v1, 1.0
	v_cvt_scalef32_pk_bf16_fp8 v182, v0, 1.0
	v_cvt_scalef32_pk_bf16_fp8 v183, v0, 1.0 op_sel:[1,0,0]
	v_cvt_scalef32_pk_bf16_fp8 v185, v1, 1.0 op_sel:[1,0,0]
	v_cvt_scalef32_pk_bf16_fp8 v201, v2, 1.0
	v_cvt_scalef32_pk_bf16_fp8 v202, v2, 1.0 op_sel:[1,0,0]
	v_cvt_scalef32_pk_bf16_fp8 v203, v3, 1.0
	v_cvt_scalef32_pk_bf16_fp8 v204, v3, 1.0 op_sel:[1,0,0]
	v_dot2_f32_bf16 v206, v182, v64, 0
	v_dot2_f32_bf16 v206, v183, v65, v206
	v_dot2_f32_bf16 v206, v184, v66, v206
	v_dot2_f32_bf16 v206, v185, v67, v206
	v_dot2_f32_bf16 v206, v201, v68, v206
	v_dot2_f32_bf16 v206, v202, v69, v206
	v_dot2_f32_bf16 v206, v203, v70, v206
	v_dot2_f32_bf16 v206, v204, v71, v206
	v_cvt_scalef32_pk_bf16_fp8 v184, v13, 1.0
	v_cvt_scalef32_pk_bf16_fp8 v182, v12, 1.0
	v_cvt_scalef32_pk_bf16_fp8 v183, v12, 1.0 op_sel:[1,0,0]
	v_cvt_scalef32_pk_bf16_fp8 v185, v13, 1.0 op_sel:[1,0,0]
	v_cvt_scalef32_pk_bf16_fp8 v201, v14, 1.0
	v_cvt_scalef32_pk_bf16_fp8 v202, v14, 1.0 op_sel:[1,0,0]
	v_cvt_scalef32_pk_bf16_fp8 v203, v15, 1.0
	v_cvt_scalef32_pk_bf16_fp8 v204, v15, 1.0 op_sel:[1,0,0]
	v_dot2_f32_bf16 v207, v182, v64, 0
	v_dot2_f32_bf16 v207, v183, v65, v207
	v_dot2_f32_bf16 v207, v184, v66, v207
	v_dot2_f32_bf16 v207, v185, v67, v207
	v_dot2_f32_bf16 v207, v201, v68, v207
	v_dot2_f32_bf16 v207, v202, v69, v207
	v_dot2_f32_bf16 v207, v203, v70, v207
	v_dot2_f32_bf16 v207, v204, v71, v207
	v_cvt_scalef32_pk_bf16_fp8 v184, v9, 1.0
	v_cvt_scalef32_pk_bf16_fp8 v182, v8, 1.0
	v_cvt_scalef32_pk_bf16_fp8 v183, v8, 1.0 op_sel:[1,0,0]
	v_cvt_scalef32_pk_bf16_fp8 v185, v9, 1.0 op_sel:[1,0,0]
	v_cvt_scalef32_pk_bf16_fp8 v201, v10, 1.0
	v_cvt_scalef32_pk_bf16_fp8 v202, v10, 1.0 op_sel:[1,0,0]
	v_cvt_scalef32_pk_bf16_fp8 v203, v11, 1.0
	v_cvt_scalef32_pk_bf16_fp8 v204, v11, 1.0 op_sel:[1,0,0]
	v_dot2_f32_bf16 v208, v182, v64, 0
	v_dot2_f32_bf16 v208, v183, v65, v208
	v_dot2_f32_bf16 v208, v184, v66, v208
	v_dot2_f32_bf16 v208, v185, v67, v208
	v_dot2_f32_bf16 v208, v201, v68, v208
	v_dot2_f32_bf16 v208, v202, v69, v208
	v_dot2_f32_bf16 v208, v203, v70, v208
	v_dot2_f32_bf16 v208, v204, v71, v208
	v_cvt_scalef32_pk_bf16_fp8 v184, v21, 1.0
	v_cvt_scalef32_pk_bf16_fp8 v182, v20, 1.0
	v_cvt_scalef32_pk_bf16_fp8 v183, v20, 1.0 op_sel:[1,0,0]
	v_cvt_scalef32_pk_bf16_fp8 v185, v21, 1.0 op_sel:[1,0,0]
	v_cvt_scalef32_pk_bf16_fp8 v201, v22, 1.0
	v_cvt_scalef32_pk_bf16_fp8 v202, v22, 1.0 op_sel:[1,0,0]
	v_cvt_scalef32_pk_bf16_fp8 v203, v23, 1.0
	v_cvt_scalef32_pk_bf16_fp8 v204, v23, 1.0 op_sel:[1,0,0]
	v_dot2_f32_bf16 v209, v182, v64, 0
	v_dot2_f32_bf16 v209, v183, v65, v209
	v_dot2_f32_bf16 v209, v184, v66, v209
	v_dot2_f32_bf16 v209, v185, v67, v209
	v_dot2_f32_bf16 v209, v201, v68, v209
	v_dot2_f32_bf16 v209, v202, v69, v209
	v_dot2_f32_bf16 v209, v203, v70, v209
	v_dot2_f32_bf16 v209, v204, v71, v209
	v_cvt_scalef32_pk_bf16_fp8 v184, v17, 1.0
	v_cvt_scalef32_pk_bf16_fp8 v182, v16, 1.0
	v_cvt_scalef32_pk_bf16_fp8 v183, v16, 1.0 op_sel:[1,0,0]
	v_cvt_scalef32_pk_bf16_fp8 v185, v17, 1.0 op_sel:[1,0,0]
	v_cvt_scalef32_pk_bf16_fp8 v201, v18, 1.0
	v_cvt_scalef32_pk_bf16_fp8 v202, v18, 1.0 op_sel:[1,0,0]
	v_cvt_scalef32_pk_bf16_fp8 v203, v19, 1.0
	v_cvt_scalef32_pk_bf16_fp8 v204, v19, 1.0 op_sel:[1,0,0]
	v_dot2_f32_bf16 v210, v182, v64, 0
	v_dot2_f32_bf16 v210, v183, v65, v210
	v_dot2_f32_bf16 v210, v184, v66, v210
	v_dot2_f32_bf16 v210, v185, v67, v210
	v_dot2_f32_bf16 v210, v201, v68, v210
	v_dot2_f32_bf16 v210, v202, v69, v210
	v_dot2_f32_bf16 v210, v203, v70, v210
	v_dot2_f32_bf16 v210, v204, v71, v210
	v_cvt_scalef32_pk_bf16_fp8 v184, v29, 1.0
	v_cvt_scalef32_pk_bf16_fp8 v182, v28, 1.0
	v_cvt_scalef32_pk_bf16_fp8 v183, v28, 1.0 op_sel:[1,0,0]
	v_cvt_scalef32_pk_bf16_fp8 v185, v29, 1.0 op_sel:[1,0,0]
	v_cvt_scalef32_pk_bf16_fp8 v201, v30, 1.0
	v_cvt_scalef32_pk_bf16_fp8 v202, v30, 1.0 op_sel:[1,0,0]
	v_cvt_scalef32_pk_bf16_fp8 v203, v31, 1.0
	v_cvt_scalef32_pk_bf16_fp8 v204, v31, 1.0 op_sel:[1,0,0]
	v_dot2_f32_bf16 v211, v182, v64, 0
	v_dot2_f32_bf16 v211, v183, v65, v211
	v_dot2_f32_bf16 v211, v184, v66, v211
	v_dot2_f32_bf16 v211, v185, v67, v211
	v_dot2_f32_bf16 v211, v201, v68, v211
	v_dot2_f32_bf16 v211, v202, v69, v211
	v_dot2_f32_bf16 v211, v203, v70, v211
	v_dot2_f32_bf16 v211, v204, v71, v211
	v_cvt_scalef32_pk_bf16_fp8 v184, v25, 1.0
	v_cvt_scalef32_pk_bf16_fp8 v182, v24, 1.0
	v_cvt_scalef32_pk_bf16_fp8 v183, v24, 1.0 op_sel:[1,0,0]
	v_cvt_scalef32_pk_bf16_fp8 v185, v25, 1.0 op_sel:[1,0,0]
	v_cvt_scalef32_pk_bf16_fp8 v201, v26, 1.0
	v_cvt_scalef32_pk_bf16_fp8 v202, v26, 1.0 op_sel:[1,0,0]
	v_cvt_scalef32_pk_bf16_fp8 v204, v27, 1.0
	v_cvt_scalef32_pk_bf16_fp8 v212, v27, 1.0 op_sel:[1,0,0]
	v_dot2_f32_bf16 v213, v182, v64, 0
	v_dot2_f32_bf16 v213, v183, v65, v213
	v_dot2_f32_bf16 v213, v184, v66, v213
	v_dot2_f32_bf16 v213, v185, v67, v213
	v_dot2_f32_bf16 v213, v201, v68, v213
	v_dot2_f32_bf16 v213, v202, v69, v213
	v_dot2_f32_bf16 v213, v204, v70, v213
	v_dot2_f32_bf16 v213, v212, v71, v213
	v_cndmask_b32_e64 v184, v206, v210, s[8:9]
	ds_bpermute_b32 v184, v193, v184
	v_cndmask_b32_e64 v185, v207, v211, s[8:9]
	v_cndmask_b32_e64 v203, v205, v209, s[8:9]
	ds_bpermute_b32 v185, v193, v185
	v_cndmask_b32_e64 v201, v208, v213, s[8:9]
	ds_bpermute_b32 v203, v193, v203
	ds_bpermute_b32 v201, v193, v201
	v_cndmask_b32_e64 v183, v210, v206, s[8:9]
	s_waitcnt lgkmcnt(3)
; DI float dot16(const unsigned (&a)[8], u32x4 b0, u32x4 b1) {
;     float acc;
;     asm volatile("v_dot2_f32_bf16 %0, %1, %9, 0\n\tv_dot2_f32_bf16 %0, %2, %10, %0\n\tv_dot2_f32_bf16 %0, %3, %11, %0\n\tv_dot2_f32_bf16 %0, %4, %12, %0\n\t"
;                  "v_dot2_f32_bf16 %0, %5, %13, %0\n\tv_dot2_f32_bf16 %0, %6, %14, %0\n\tv_dot2_f32_bf16 %0, %7, %15, %0\n\tv_dot2_f32_bf16 %0, %8, %16, %0\n\ts_nop 2"
;                  : "=&v"(acc)
;                  : "v"(a[0]), "v"(a[1]), "v"(a[2]), "v"(a[3]), "v"(a[4]), "v"(a[5]), "v"(a[6]), "v"(a[7]),
;                    "v"(b0.x), "v"(b0.y), "v"(b0.z), "v"(b0.w), "v"(b1.x), "v"(b1.y), "v"(b1.z), "v"(b1.w));
;     return acc;
; }
; DI float dot_fp8_row(u32x4 u, u32x4 xa, u32x4 xb) {
;     unsigned a[8];
; #pragma unroll
;     for (int j = 0; j < 4; ++j) {
;         a[2 * j] = __builtin_bit_cast(unsigned, __builtin_amdgcn_cvt_scalef32_pk_bf16_fp8(u[j], 1.0f, false));
;         a[2 * j + 1] = __builtin_bit_cast(unsigned, __builtin_amdgcn_cvt_scalef32_pk_bf16_fp8(u[j], 1.0f, true));
;     }
;     return dot16(a, xa, xb);
; }
	v_add_f32_e32 v183, v183, v184
	v_cndmask_b32_e64 v184, v211, v207, s[8:9]
	v_cndmask_b32_e64 v182, v209, v205, s[8:9]
	s_waitcnt lgkmcnt(2)
	v_add_f32_e32 v184, v184, v185
	v_cndmask_b32_e64 v185, v213, v208, s[8:9]
	s_waitcnt lgkmcnt(1)
	v_add_f32_e32 v182, v182, v203
	s_waitcnt lgkmcnt(0)
	v_add_f32_e32 v185, v185, v201
	v_cndmask_b32_e64 v201, v182, v184, s[10:11]
	v_cndmask_b32_e64 v202, v183, v185, s[10:11]
	ds_bpermute_b32 v201, v194, v201
	ds_bpermute_b32 v202, v194, v202
	v_cndmask_b32_e64 v182, v184, v182, s[10:11]
	v_cndmask_b32_e64 v183, v185, v183, s[10:11]
	v_cvt_scalef32_pk_bf16_fp8 v185, v36, 1.0
	s_waitcnt lgkmcnt(1)
	v_add_f32_e32 v182, v182, v201
	s_waitcnt lgkmcnt(0)
	v_add_f32_e32 v183, v183, v202
	v_cvt_scalef32_pk_bf16_fp8 v201, v36, 1.0 op_sel:[1,0,0]
	v_cvt_scalef32_pk_bf16_fp8 v202, v37, 1.0
	v_cvt_scalef32_pk_bf16_fp8 v203, v37, 1.0 op_sel:[1,0,0]
	v_cvt_scalef32_pk_bf16_fp8 v204, v38, 1.0
	v_cvt_scalef32_pk_bf16_fp8 v205, v38, 1.0 op_sel:[1,0,0]
	v_cvt_scalef32_pk_bf16_fp8 v207, v39, 1.0 op_sel:[1,0,0]
	v_cvt_scalef32_pk_bf16_fp8 v206, v39, 1.0
	v_dot2_f32_bf16 v208, v185, v64, 0
	v_dot2_f32_bf16 v208, v201, v65, v208
	v_dot2_f32_bf16 v208, v202, v66, v208
	v_dot2_f32_bf16 v208, v203, v67, v208
	v_dot2_f32_bf16 v208, v204, v68, v208
	v_dot2_f32_bf16 v208, v205, v69, v208
	v_dot2_f32_bf16 v208, v206, v70, v208
	v_dot2_f32_bf16 v208, v207, v71, v208
	v_cvt_scalef32_pk_bf16_fp8 v185, v32, 1.0
	v_cvt_scalef32_pk_bf16_fp8 v201, v32, 1.0 op_sel:[1,0,0]
	v_cvt_scalef32_pk_bf16_fp8 v202, v33, 1.0
	v_cvt_scalef32_pk_bf16_fp8 v203, v33, 1.0 op_sel:[1,0,0]
	v_cvt_scalef32_pk_bf16_fp8 v204, v34, 1.0
	v_cvt_scalef32_pk_bf16_fp8 v205, v34, 1.0 op_sel:[1,0,0]
	v_cvt_scalef32_pk_bf16_fp8 v207, v35, 1.0 op_sel:[1,0,0]
	v_cvt_scalef32_pk_bf16_fp8 v206, v35, 1.0
	v_dot2_f32_bf16 v209, v185, v64, 0
	v_dot2_f32_bf16 v209, v201, v65, v209
	v_dot2_f32_bf16 v209, v202, v66, v209
	v_dot2_f32_bf16 v209, v203, v67, v209
	v_dot2_f32_bf16 v209, v204, v68, v209
	v_dot2_f32_bf16 v209, v205, v69, v209
	v_dot2_f32_bf16 v209, v206, v70, v209
	v_dot2_f32_bf16 v209, v207, v71, v209
	v_cvt_scalef32_pk_bf16_fp8 v185, v44, 1.0
	v_cvt_scalef32_pk_bf16_fp8 v201, v44, 1.0 op_sel:[1,0,0]
	v_cvt_scalef32_pk_bf16_fp8 v202, v45, 1.0
	v_cvt_scalef32_pk_bf16_fp8 v203, v45, 1.0 op_sel:[1,0,0]
	v_cvt_scalef32_pk_bf16_fp8 v204, v46, 1.0
	v_cvt_scalef32_pk_bf16_fp8 v205, v46, 1.0 op_sel:[1,0,0]
	v_cvt_scalef32_pk_bf16_fp8 v207, v47, 1.0 op_sel:[1,0,0]
	v_cvt_scalef32_pk_bf16_fp8 v206, v47, 1.0
	v_dot2_f32_bf16 v210, v185, v64, 0
	v_dot2_f32_bf16 v210, v201, v65, v210
	v_dot2_f32_bf16 v210, v202, v66, v210
	v_dot2_f32_bf16 v210, v203, v67, v210
	v_dot2_f32_bf16 v210, v204, v68, v210
	v_dot2_f32_bf16 v210, v205, v69, v210
	v_dot2_f32_bf16 v210, v206, v70, v210
	v_dot2_f32_bf16 v210, v207, v71, v210
	v_cvt_scalef32_pk_bf16_fp8 v185, v40, 1.0
	v_cvt_scalef32_pk_bf16_fp8 v201, v40, 1.0 op_sel:[1,0,0]
	v_cvt_scalef32_pk_bf16_fp8 v202, v41, 1.0
	v_cvt_scalef32_pk_bf16_fp8 v203, v41, 1.0 op_sel:[1,0,0]
	v_cvt_scalef32_pk_bf16_fp8 v204, v42, 1.0
	v_cvt_scalef32_pk_bf16_fp8 v205, v42, 1.0 op_sel:[1,0,0]
	v_cvt_scalef32_pk_bf16_fp8 v207, v43, 1.0 op_sel:[1,0,0]
	v_cvt_scalef32_pk_bf16_fp8 v206, v43, 1.0
	v_dot2_f32_bf16 v211, v185, v64, 0
	v_dot2_f32_bf16 v211, v201, v65, v211
	v_dot2_f32_bf16 v211, v202, v66, v211
	v_dot2_f32_bf16 v211, v203, v67, v211
	v_dot2_f32_bf16 v211, v204, v68, v211
	v_dot2_f32_bf16 v211, v205, v69, v211
	v_dot2_f32_bf16 v211, v206, v70, v211
	v_dot2_f32_bf16 v211, v207, v71, v211
	v_cvt_scalef32_pk_bf16_fp8 v185, v52, 1.0
	v_cvt_scalef32_pk_bf16_fp8 v201, v52, 1.0 op_sel:[1,0,0]
	v_cvt_scalef32_pk_bf16_fp8 v202, v53, 1.0
	v_cvt_scalef32_pk_bf16_fp8 v203, v53, 1.0 op_sel:[1,0,0]
	v_cvt_scalef32_pk_bf16_fp8 v204, v54, 1.0
	v_cvt_scalef32_pk_bf16_fp8 v205, v54, 1.0 op_sel:[1,0,0]
	v_cvt_scalef32_pk_bf16_fp8 v207, v55, 1.0 op_sel:[1,0,0]
	v_cvt_scalef32_pk_bf16_fp8 v206, v55, 1.0
	v_dot2_f32_bf16 v212, v185, v64, 0
	v_dot2_f32_bf16 v212, v201, v65, v212
	v_dot2_f32_bf16 v212, v202, v66, v212
	v_dot2_f32_bf16 v212, v203, v67, v212
	v_dot2_f32_bf16 v212, v204, v68, v212
	v_dot2_f32_bf16 v212, v205, v69, v212
	v_dot2_f32_bf16 v212, v206, v70, v212
	v_dot2_f32_bf16 v212, v207, v71, v212
	v_cvt_scalef32_pk_bf16_fp8 v185, v48, 1.0
	v_cvt_scalef32_pk_bf16_fp8 v201, v48, 1.0 op_sel:[1,0,0]
	v_cvt_scalef32_pk_bf16_fp8 v202, v49, 1.0
	v_cvt_scalef32_pk_bf16_fp8 v203, v49, 1.0 op_sel:[1,0,0]
	v_cvt_scalef32_pk_bf16_fp8 v204, v50, 1.0
	v_cvt_scalef32_pk_bf16_fp8 v205, v50, 1.0 op_sel:[1,0,0]
	v_cvt_scalef32_pk_bf16_fp8 v207, v51, 1.0 op_sel:[1,0,0]
	v_cvt_scalef32_pk_bf16_fp8 v206, v51, 1.0
	v_dot2_f32_bf16 v213, v185, v64, 0
	v_dot2_f32_bf16 v213, v201, v65, v213
	v_dot2_f32_bf16 v213, v202, v66, v213
	v_dot2_f32_bf16 v213, v203, v67, v213
	v_dot2_f32_bf16 v213, v204, v68, v213
	v_dot2_f32_bf16 v213, v205, v69, v213
	v_dot2_f32_bf16 v213, v206, v70, v213
	v_dot2_f32_bf16 v213, v207, v71, v213
	v_cvt_scalef32_pk_bf16_fp8 v185, v60, 1.0
	v_cvt_scalef32_pk_bf16_fp8 v201, v60, 1.0 op_sel:[1,0,0]
	v_cvt_scalef32_pk_bf16_fp8 v202, v61, 1.0
	v_cvt_scalef32_pk_bf16_fp8 v203, v61, 1.0 op_sel:[1,0,0]
	v_cvt_scalef32_pk_bf16_fp8 v204, v62, 1.0
	v_cvt_scalef32_pk_bf16_fp8 v205, v62, 1.0 op_sel:[1,0,0]
	v_cvt_scalef32_pk_bf16_fp8 v207, v63, 1.0 op_sel:[1,0,0]
	v_cvt_scalef32_pk_bf16_fp8 v206, v63, 1.0
	v_dot2_f32_bf16 v214, v185, v64, 0
	v_dot2_f32_bf16 v214, v201, v65, v214
	v_dot2_f32_bf16 v214, v202, v66, v214
	v_dot2_f32_bf16 v214, v203, v67, v214
	v_dot2_f32_bf16 v214, v204, v68, v214
	v_dot2_f32_bf16 v214, v205, v69, v214
	v_dot2_f32_bf16 v214, v206, v70, v214
	v_dot2_f32_bf16 v214, v207, v71, v214
	v_cvt_scalef32_pk_bf16_fp8 v185, v56, 1.0
	v_cvt_scalef32_pk_bf16_fp8 v201, v56, 1.0 op_sel:[1,0,0]
	v_cvt_scalef32_pk_bf16_fp8 v202, v57, 1.0
	v_cvt_scalef32_pk_bf16_fp8 v203, v57, 1.0 op_sel:[1,0,0]
	v_cvt_scalef32_pk_bf16_fp8 v204, v58, 1.0
	v_cvt_scalef32_pk_bf16_fp8 v205, v58, 1.0 op_sel:[1,0,0]
	v_cvt_scalef32_pk_bf16_fp8 v207, v59, 1.0
	v_cvt_scalef32_pk_bf16_fp8 v215, v59, 1.0 op_sel:[1,0,0]
	v_dot2_f32_bf16 v216, v185, v64, 0
	v_dot2_f32_bf16 v216, v201, v65, v216
	v_dot2_f32_bf16 v216, v202, v66, v216
	v_dot2_f32_bf16 v216, v203, v67, v216
	v_dot2_f32_bf16 v216, v204, v68, v216
	v_dot2_f32_bf16 v216, v205, v69, v216
	v_dot2_f32_bf16 v216, v207, v70, v216
	v_dot2_f32_bf16 v216, v215, v71, v216
	v_cndmask_b32_e64 v66, v209, v213, s[8:9]
	ds_bpermute_b32 v66, v193, v66
	v_cndmask_b32_e64 v67, v210, v214, s[8:9]
	v_cndmask_b32_e64 v206, v208, v212, s[8:9]
	ds_bpermute_b32 v67, v193, v67
	v_cndmask_b32_e64 v68, v211, v216, s[8:9]
	ds_bpermute_b32 v206, v193, v206
	ds_bpermute_b32 v68, v193, v68
	v_cndmask_b32_e64 v65, v213, v209, s[8:9]
	s_waitcnt lgkmcnt(3)
; DI void peer_u_phase(const bf16_t* __restrict__ x1, const int* __restrict__ eidx, const unsigned char* __restrict__ U8, float* __restrict__ ph) {
;     ...
;                 xa = xan; xb = xbn;
	v_add_f32_e32 v65, v65, v66
	v_cndmask_b32_e64 v66, v214, v210, s[8:9]
	v_cndmask_b32_e64 v64, v212, v208, s[8:9]
	s_waitcnt lgkmcnt(2)
	v_add_f32_e32 v66, v66, v67
	v_cndmask_b32_e64 v67, v216, v211, s[8:9]
	s_waitcnt lgkmcnt(1)
	v_add_f32_e32 v64, v64, v206
	s_waitcnt lgkmcnt(0)
	v_add_f32_e32 v67, v67, v68
	v_cndmask_b32_e64 v68, v64, v66, s[10:11]
	v_cndmask_b32_e64 v69, v65, v67, s[10:11]
	ds_bpermute_b32 v68, v194, v68
	ds_bpermute_b32 v69, v194, v69
	v_cndmask_b32_e64 v64, v66, v64, s[10:11]
	v_cndmask_b32_e64 v65, v67, v65, s[10:11]
	v_cndmask_b32_e64 v184, v182, v183, s[12:13]
	s_waitcnt lgkmcnt(1)
	v_add_f32_e32 v64, v64, v68
	s_waitcnt lgkmcnt(0)
	v_add_f32_e32 v65, v65, v69
	v_cndmask_b32_e64 v66, v64, v65, s[12:13]
	ds_bpermute_b32 v70, v195, v184
	ds_bpermute_b32 v66, v195, v66
	v_cndmask_b32_e64 v67, v183, v182, s[12:13]
	v_cndmask_b32_e64 v64, v65, v64, s[12:13]
	s_waitcnt lgkmcnt(1)
	v_add_f32_e32 v67, v67, v70
	s_waitcnt lgkmcnt(0)
	v_add_f32_e32 v66, v64, v66
	s_setprio 0
	v_lshlrev_b64 v[64:65], 12, v[180:181]
	v_lshl_add_u64 v[64:65], v[178:179], 0, v[64:65]
	global_store_dword v[64:65], v67, off
	global_store_dword v[64:65], v66, off offset:256
	s_waitcnt vmcnt(2)
	v_mov_b64_e32 v[64:65], v[72:73]
	v_mov_b64_e32 v[68:69], v[140:141]
	v_mov_b64_e32 v[66:67], v[74:75]
	v_mov_b64_e32 v[70:71], v[142:143]

; DI float dot16(const unsigned (&a)[8], u32x4 b0, u32x4 b1) {
;     float acc;
;     asm volatile("v_dot2_f32_bf16 %0, %1, %9, 0\n\tv_dot2_f32_bf16 %0, %2, %10, %0\n\tv_dot2_f32_bf16 %0, %3, %11, %0\n\tv_dot2_f32_bf16 %0, %4, %12, %0\n\t"
;                  "v_dot2_f32_bf16 %0, %5, %13, %0\n\tv_dot2_f32_bf16 %0, %6, %14, %0\n\tv_dot2_f32_bf16 %0, %7, %15, %0\n\tv_dot2_f32_bf16 %0, %8, %16, %0\n\ts_nop 2"
;                  : "=&v"(acc)
;                  : "v"(a[0]), "v"(a[1]), "v"(a[2]), "v"(a[3]), "v"(a[4]), "v"(a[5]), "v"(a[6]), "v"(a[7]),
;                    "v"(b0.x), "v"(b0.y), "v"(b0.z), "v"(b0.w), "v"(b1.x), "v"(b1.y), "v"(b1.z), "v"(b1.w));
;     return acc;
; }
; DI float dot_fp8_row(u32x4 u, u32x4 xa, u32x4 xb) {
;     unsigned a[8];
; #pragma unroll
;     for (int j = 0; j < 4; ++j) {
;         a[2 * j] = __builtin_bit_cast(unsigned, __builtin_amdgcn_cvt_scalef32_pk_bf16_fp8(u[j], 1.0f, false));
;         a[2 * j + 1] = __builtin_bit_cast(unsigned, __builtin_amdgcn_cvt_scalef32_pk_bf16_fp8(u[j], 1.0f, true));
;     }
;     return dot16(a, xa, xb);
; }
.LBB0_1233:
	s_or_b64 exec, exec, s[0:1]
	s_setprio 1
	s_waitcnt vmcnt(15)
	v_cvt_scalef32_pk_bf16_fp8 v203, v77, 1.0
	v_cvt_scalef32_pk_bf16_fp8 v183, v76, 1.0
	v_cvt_scalef32_pk_bf16_fp8 v202, v76, 1.0 op_sel:[1,0,0]
	v_cvt_scalef32_pk_bf16_fp8 v204, v77, 1.0 op_sel:[1,0,0]
	v_cvt_scalef32_pk_bf16_fp8 v205, v78, 1.0
	v_cvt_scalef32_pk_bf16_fp8 v206, v78, 1.0 op_sel:[1,0,0]
	v_cvt_scalef32_pk_bf16_fp8 v207, v79, 1.0
	v_cvt_scalef32_pk_bf16_fp8 v208, v79, 1.0 op_sel:[1,0,0]
	v_dot2_f32_bf16 v209, v183, v72, 0
	v_dot2_f32_bf16 v209, v202, v73, v209
	v_dot2_f32_bf16 v209, v203, v74, v209
	v_dot2_f32_bf16 v209, v204, v75, v209
	v_dot2_f32_bf16 v209, v205, v140, v209
	v_dot2_f32_bf16 v209, v206, v141, v209
	v_dot2_f32_bf16 v209, v207, v142, v209
	v_dot2_f32_bf16 v209, v208, v143, v209
	s_waitcnt vmcnt(14)
	v_cvt_scalef32_pk_bf16_fp8 v203, v81, 1.0
	v_cvt_scalef32_pk_bf16_fp8 v183, v80, 1.0
	v_cvt_scalef32_pk_bf16_fp8 v202, v80, 1.0 op_sel:[1,0,0]
	v_cvt_scalef32_pk_bf16_fp8 v204, v81, 1.0 op_sel:[1,0,0]
	v_cvt_scalef32_pk_bf16_fp8 v205, v82, 1.0
	v_cvt_scalef32_pk_bf16_fp8 v206, v82, 1.0 op_sel:[1,0,0]
	v_cvt_scalef32_pk_bf16_fp8 v207, v83, 1.0
	v_cvt_scalef32_pk_bf16_fp8 v208, v83, 1.0 op_sel:[1,0,0]
	v_dot2_f32_bf16 v210, v183, v72, 0
	v_dot2_f32_bf16 v210, v202, v73, v210
	v_dot2_f32_bf16 v210, v203, v74, v210
	v_dot2_f32_bf16 v210, v204, v75, v210
	v_dot2_f32_bf16 v210, v205, v140, v210
	v_dot2_f32_bf16 v210, v206, v141, v210
	v_dot2_f32_bf16 v210, v207, v142, v210
	v_dot2_f32_bf16 v210, v208, v143, v210
	s_waitcnt vmcnt(13)
	v_cvt_scalef32_pk_bf16_fp8 v203, v85, 1.0
	v_cvt_scalef32_pk_bf16_fp8 v183, v84, 1.0
	v_cvt_scalef32_pk_bf16_fp8 v202, v84, 1.0 op_sel:[1,0,0]
	v_cvt_scalef32_pk_bf16_fp8 v204, v85, 1.0 op_sel:[1,0,0]
	v_cvt_scalef32_pk_bf16_fp8 v205, v86, 1.0
	v_cvt_scalef32_pk_bf16_fp8 v206, v86, 1.0 op_sel:[1,0,0]
	v_cvt_scalef32_pk_bf16_fp8 v207, v87, 1.0
	v_cvt_scalef32_pk_bf16_fp8 v208, v87, 1.0 op_sel:[1,0,0]
	v_dot2_f32_bf16 v211, v183, v72, 0
	v_dot2_f32_bf16 v211, v202, v73, v211
	v_dot2_f32_bf16 v211, v203, v74, v211
	v_dot2_f32_bf16 v211, v204, v75, v211
	v_dot2_f32_bf16 v211, v205, v140, v211
	v_dot2_f32_bf16 v211, v206, v141, v211
	v_dot2_f32_bf16 v211, v207, v142, v211
	v_dot2_f32_bf16 v211, v208, v143, v211
	s_waitcnt vmcnt(12)
	v_cvt_scalef32_pk_bf16_fp8 v203, v89, 1.0
	v_cvt_scalef32_pk_bf16_fp8 v183, v88, 1.0
	v_cvt_scalef32_pk_bf16_fp8 v202, v88, 1.0 op_sel:[1,0,0]
	v_cvt_scalef32_pk_bf16_fp8 v204, v89, 1.0 op_sel:[1,0,0]
	v_cvt_scalef32_pk_bf16_fp8 v205, v90, 1.0
	v_cvt_scalef32_pk_bf16_fp8 v206, v90, 1.0 op_sel:[1,0,0]
	v_cvt_scalef32_pk_bf16_fp8 v207, v91, 1.0
	v_cvt_scalef32_pk_bf16_fp8 v208, v91, 1.0 op_sel:[1,0,0]
	v_dot2_f32_bf16 v212, v183, v72, 0
	v_dot2_f32_bf16 v212, v202, v73, v212
	v_dot2_f32_bf16 v212, v203, v74, v212
	v_dot2_f32_bf16 v212, v204, v75, v212
	v_dot2_f32_bf16 v212, v205, v140, v212
	v_dot2_f32_bf16 v212, v206, v141, v212
	v_dot2_f32_bf16 v212, v207, v142, v212
	v_dot2_f32_bf16 v212, v208, v143, v212
	s_waitcnt vmcnt(11)
	v_cvt_scalef32_pk_bf16_fp8 v203, v93, 1.0
	v_cvt_scalef32_pk_bf16_fp8 v183, v92, 1.0
	v_cvt_scalef32_pk_bf16_fp8 v202, v92, 1.0 op_sel:[1,0,0]
	v_cvt_scalef32_pk_bf16_fp8 v204, v93, 1.0 op_sel:[1,0,0]
	v_cvt_scalef32_pk_bf16_fp8 v205, v94, 1.0
	v_cvt_scalef32_pk_bf16_fp8 v206, v94, 1.0 op_sel:[1,0,0]
	v_cvt_scalef32_pk_bf16_fp8 v207, v95, 1.0
	v_cvt_scalef32_pk_bf16_fp8 v208, v95, 1.0 op_sel:[1,0,0]
	v_dot2_f32_bf16 v213, v183, v72, 0
	v_dot2_f32_bf16 v213, v202, v73, v213
	v_dot2_f32_bf16 v213, v203, v74, v213
	v_dot2_f32_bf16 v213, v204, v75, v213
	v_dot2_f32_bf16 v213, v205, v140, v213
	v_dot2_f32_bf16 v213, v206, v141, v213
	v_dot2_f32_bf16 v213, v207, v142, v213
	v_dot2_f32_bf16 v213, v208, v143, v213
	s_waitcnt vmcnt(10)
	v_cvt_scalef32_pk_bf16_fp8 v203, v97, 1.0
	v_cvt_scalef32_pk_bf16_fp8 v183, v96, 1.0
	v_cvt_scalef32_pk_bf16_fp8 v202, v96, 1.0 op_sel:[1,0,0]
	v_cvt_scalef32_pk_bf16_fp8 v204, v97, 1.0 op_sel:[1,0,0]
	v_cvt_scalef32_pk_bf16_fp8 v205, v98, 1.0
	v_cvt_scalef32_pk_bf16_fp8 v206, v98, 1.0 op_sel:[1,0,0]
	v_cvt_scalef32_pk_bf16_fp8 v207, v99, 1.0
	v_cvt_scalef32_pk_bf16_fp8 v208, v99, 1.0 op_sel:[1,0,0]
	v_dot2_f32_bf16 v214, v183, v72, 0
	v_dot2_f32_bf16 v214, v202, v73, v214
	v_dot2_f32_bf16 v214, v203, v74, v214
	v_dot2_f32_bf16 v214, v204, v75, v214
	v_dot2_f32_bf16 v214, v205, v140, v214
	v_dot2_f32_bf16 v214, v206, v141, v214
	v_dot2_f32_bf16 v214, v207, v142, v214
	v_dot2_f32_bf16 v214, v208, v143, v214
	s_waitcnt vmcnt(9)
	v_cvt_scalef32_pk_bf16_fp8 v203, v101, 1.0
	v_cvt_scalef32_pk_bf16_fp8 v183, v100, 1.0
	v_cvt_scalef32_pk_bf16_fp8 v202, v100, 1.0 op_sel:[1,0,0]
	v_cvt_scalef32_pk_bf16_fp8 v204, v101, 1.0 op_sel:[1,0,0]
	v_cvt_scalef32_pk_bf16_fp8 v205, v102, 1.0
	v_cvt_scalef32_pk_bf16_fp8 v206, v102, 1.0 op_sel:[1,0,0]
	v_cvt_scalef32_pk_bf16_fp8 v207, v103, 1.0
	v_cvt_scalef32_pk_bf16_fp8 v208, v103, 1.0 op_sel:[1,0,0]
	v_dot2_f32_bf16 v215, v183, v72, 0
	v_dot2_f32_bf16 v215, v202, v73, v215
	v_dot2_f32_bf16 v215, v203, v74, v215
	v_dot2_f32_bf16 v215, v204, v75, v215
	v_dot2_f32_bf16 v215, v205, v140, v215
	v_dot2_f32_bf16 v215, v206, v141, v215
	v_dot2_f32_bf16 v215, v207, v142, v215
	v_dot2_f32_bf16 v215, v208, v143, v215
	s_waitcnt vmcnt(8)
; DI float dot16(const unsigned (&a)[8], u32x4 b0, u32x4 b1) {
;     float acc;
;     asm volatile("v_dot2_f32_bf16 %0, %1, %9, 0\n\tv_dot2_f32_bf16 %0, %2, %10, %0\n\tv_dot2_f32_bf16 %0, %3, %11, %0\n\tv_dot2_f32_bf16 %0, %4, %12, %0\n\t"
;                  "v_dot2_f32_bf16 %0, %5, %13, %0\n\tv_dot2_f32_bf16 %0, %6, %14, %0\n\tv_dot2_f32_bf16 %0, %7, %15, %0\n\tv_dot2_f32_bf16 %0, %8, %16, %0\n\ts_nop 2"
;                  : "=&v"(acc)
;                  : "v"(a[0]), "v"(a[1]), "v"(a[2]), "v"(a[3]), "v"(a[4]), "v"(a[5]), "v"(a[6]), "v"(a[7]),
;                    "v"(b0.x), "v"(b0.y), "v"(b0.z), "v"(b0.w), "v"(b1.x), "v"(b1.y), "v"(b1.z), "v"(b1.w));
;     return acc;
; }
; DI float dot_fp8_row(u32x4 u, u32x4 xa, u32x4 xb) {
;     unsigned a[8];
; #pragma unroll
;     for (int j = 0; j < 4; ++j) {
;         a[2 * j] = __builtin_bit_cast(unsigned, __builtin_amdgcn_cvt_scalef32_pk_bf16_fp8(u[j], 1.0f, false));
;         a[2 * j + 1] = __builtin_bit_cast(unsigned, __builtin_amdgcn_cvt_scalef32_pk_bf16_fp8(u[j], 1.0f, true));
;     }
;     return dot16(a, xa, xb);
; }
	v_cvt_scalef32_pk_bf16_fp8 v203, v105, 1.0
	v_cvt_scalef32_pk_bf16_fp8 v183, v104, 1.0
	v_cvt_scalef32_pk_bf16_fp8 v202, v104, 1.0 op_sel:[1,0,0]
	v_cvt_scalef32_pk_bf16_fp8 v204, v105, 1.0 op_sel:[1,0,0]
	v_cvt_scalef32_pk_bf16_fp8 v205, v106, 1.0
	v_cvt_scalef32_pk_bf16_fp8 v206, v106, 1.0 op_sel:[1,0,0]
	v_cvt_scalef32_pk_bf16_fp8 v208, v107, 1.0
	v_cvt_scalef32_pk_bf16_fp8 v216, v107, 1.0 op_sel:[1,0,0]
	v_dot2_f32_bf16 v217, v183, v72, 0
	v_dot2_f32_bf16 v217, v202, v73, v217
	v_dot2_f32_bf16 v217, v203, v74, v217
	v_dot2_f32_bf16 v217, v204, v75, v217
	v_dot2_f32_bf16 v217, v205, v140, v217
	v_dot2_f32_bf16 v217, v206, v141, v217
	v_dot2_f32_bf16 v217, v208, v142, v217
	v_dot2_f32_bf16 v217, v216, v143, v217
	v_cndmask_b32_e64 v203, v210, v214, s[8:9]
	ds_bpermute_b32 v203, v193, v203
	v_cndmask_b32_e64 v204, v211, v215, s[8:9]
	ds_bpermute_b32 v204, v193, v204
	v_cndmask_b32_e64 v205, v212, v217, s[8:9]
	v_cndmask_b32_e64 v207, v209, v213, s[8:9]
	ds_bpermute_b32 v205, v193, v205
	ds_bpermute_b32 v207, v193, v207
	v_cndmask_b32_e64 v202, v214, v210, s[8:9]
	s_waitcnt lgkmcnt(3)
	v_add_f32_e32 v202, v202, v203
	v_cndmask_b32_e64 v203, v215, v211, s[8:9]
	s_waitcnt lgkmcnt(2)
	v_add_f32_e32 v203, v203, v204
	v_cndmask_b32_e64 v204, v217, v212, s[8:9]
	v_cndmask_b32_e64 v183, v213, v209, s[8:9]
	s_waitcnt lgkmcnt(1)
	v_add_f32_e32 v204, v204, v205
	s_waitcnt lgkmcnt(0)
	v_add_f32_e32 v183, v183, v207
	v_cndmask_b32_e64 v206, v202, v204, s[10:11]
	v_cndmask_b32_e64 v205, v183, v203, s[10:11]
	ds_bpermute_b32 v206, v194, v206
	ds_bpermute_b32 v205, v194, v205
	v_cndmask_b32_e64 v202, v204, v202, s[10:11]
	v_cndmask_b32_e64 v183, v203, v183, s[10:11]
	s_waitcnt vmcnt(7)
	v_cvt_scalef32_pk_bf16_fp8 v204, v108, 1.0
	s_waitcnt lgkmcnt(1)
	v_add_f32_e32 v202, v202, v206
	v_cvt_scalef32_pk_bf16_fp8 v206, v109, 1.0
	s_waitcnt lgkmcnt(0)
	v_add_f32_e32 v183, v183, v205
	v_cvt_scalef32_pk_bf16_fp8 v205, v108, 1.0 op_sel:[1,0,0]
	v_cvt_scalef32_pk_bf16_fp8 v207, v109, 1.0 op_sel:[1,0,0]
	v_cvt_scalef32_pk_bf16_fp8 v208, v110, 1.0
	v_cvt_scalef32_pk_bf16_fp8 v209, v110, 1.0 op_sel:[1,0,0]
	v_cvt_scalef32_pk_bf16_fp8 v210, v111, 1.0
	v_cvt_scalef32_pk_bf16_fp8 v211, v111, 1.0 op_sel:[1,0,0]
	v_dot2_f32_bf16 v212, v204, v72, 0
	v_dot2_f32_bf16 v212, v205, v73, v212
	v_dot2_f32_bf16 v212, v206, v74, v212
	v_dot2_f32_bf16 v212, v207, v75, v212
	v_dot2_f32_bf16 v212, v208, v140, v212
	v_dot2_f32_bf16 v212, v209, v141, v212
	v_dot2_f32_bf16 v212, v210, v142, v212
	v_dot2_f32_bf16 v212, v211, v143, v212
	s_waitcnt vmcnt(6)
	v_cvt_scalef32_pk_bf16_fp8 v206, v113, 1.0
	v_cvt_scalef32_pk_bf16_fp8 v204, v112, 1.0
	v_cvt_scalef32_pk_bf16_fp8 v205, v112, 1.0 op_sel:[1,0,0]
	v_cvt_scalef32_pk_bf16_fp8 v207, v113, 1.0 op_sel:[1,0,0]
	v_cvt_scalef32_pk_bf16_fp8 v208, v114, 1.0
	v_cvt_scalef32_pk_bf16_fp8 v209, v114, 1.0 op_sel:[1,0,0]
	v_cvt_scalef32_pk_bf16_fp8 v210, v115, 1.0
	v_cvt_scalef32_pk_bf16_fp8 v211, v115, 1.0 op_sel:[1,0,0]
	v_dot2_f32_bf16 v213, v204, v72, 0
	v_dot2_f32_bf16 v213, v205, v73, v213
	v_dot2_f32_bf16 v213, v206, v74, v213
	v_dot2_f32_bf16 v213, v207, v75, v213
	v_dot2_f32_bf16 v213, v208, v140, v213
	v_dot2_f32_bf16 v213, v209, v141, v213
	v_dot2_f32_bf16 v213, v210, v142, v213
	v_dot2_f32_bf16 v213, v211, v143, v213
	s_waitcnt vmcnt(5)
	v_cvt_scalef32_pk_bf16_fp8 v206, v117, 1.0
	v_cvt_scalef32_pk_bf16_fp8 v204, v116, 1.0
	v_cvt_scalef32_pk_bf16_fp8 v205, v116, 1.0 op_sel:[1,0,0]
	v_cvt_scalef32_pk_bf16_fp8 v207, v117, 1.0 op_sel:[1,0,0]
	v_cvt_scalef32_pk_bf16_fp8 v208, v118, 1.0
	v_cvt_scalef32_pk_bf16_fp8 v209, v118, 1.0 op_sel:[1,0,0]
	v_cvt_scalef32_pk_bf16_fp8 v210, v119, 1.0
	v_cvt_scalef32_pk_bf16_fp8 v211, v119, 1.0 op_sel:[1,0,0]
	v_dot2_f32_bf16 v214, v204, v72, 0
	v_dot2_f32_bf16 v214, v205, v73, v214
	v_dot2_f32_bf16 v214, v206, v74, v214
	v_dot2_f32_bf16 v214, v207, v75, v214
	v_dot2_f32_bf16 v214, v208, v140, v214
	v_dot2_f32_bf16 v214, v209, v141, v214
	v_dot2_f32_bf16 v214, v210, v142, v214
	v_dot2_f32_bf16 v214, v211, v143, v214
	s_waitcnt vmcnt(4)
	v_cvt_scalef32_pk_bf16_fp8 v206, v121, 1.0
	v_cvt_scalef32_pk_bf16_fp8 v204, v120, 1.0
	v_cvt_scalef32_pk_bf16_fp8 v205, v120, 1.0 op_sel:[1,0,0]
	v_cvt_scalef32_pk_bf16_fp8 v207, v121, 1.0 op_sel:[1,0,0]
	v_cvt_scalef32_pk_bf16_fp8 v208, v122, 1.0
	v_cvt_scalef32_pk_bf16_fp8 v209, v122, 1.0 op_sel:[1,0,0]
	v_cvt_scalef32_pk_bf16_fp8 v210, v123, 1.0
	v_cvt_scalef32_pk_bf16_fp8 v211, v123, 1.0 op_sel:[1,0,0]
	v_dot2_f32_bf16 v215, v204, v72, 0
	v_dot2_f32_bf16 v215, v205, v73, v215
	v_dot2_f32_bf16 v215, v206, v74, v215
	v_dot2_f32_bf16 v215, v207, v75, v215
	v_dot2_f32_bf16 v215, v208, v140, v215
	v_dot2_f32_bf16 v215, v209, v141, v215
	v_dot2_f32_bf16 v215, v210, v142, v215
	v_dot2_f32_bf16 v215, v211, v143, v215
	s_waitcnt vmcnt(3)
	v_cvt_scalef32_pk_bf16_fp8 v206, v125, 1.0
	v_cvt_scalef32_pk_bf16_fp8 v204, v124, 1.0
	v_cvt_scalef32_pk_bf16_fp8 v205, v124, 1.0 op_sel:[1,0,0]
	v_cvt_scalef32_pk_bf16_fp8 v207, v125, 1.0 op_sel:[1,0,0]
	v_cvt_scalef32_pk_bf16_fp8 v208, v126, 1.0
	v_cvt_scalef32_pk_bf16_fp8 v209, v126, 1.0 op_sel:[1,0,0]
	v_cvt_scalef32_pk_bf16_fp8 v210, v127, 1.0
	v_cvt_scalef32_pk_bf16_fp8 v211, v127, 1.0 op_sel:[1,0,0]
	v_dot2_f32_bf16 v216, v204, v72, 0
	v_dot2_f32_bf16 v216, v205, v73, v216
	v_dot2_f32_bf16 v216, v206, v74, v216
	v_dot2_f32_bf16 v216, v207, v75, v216
	v_dot2_f32_bf16 v216, v208, v140, v216
	v_dot2_f32_bf16 v216, v209, v141, v216
	v_dot2_f32_bf16 v216, v210, v142, v216
	v_dot2_f32_bf16 v216, v211, v143, v216
	s_waitcnt vmcnt(2)
; #define U_ISSUE(SEG, E0, E1) { _Pragma("unroll") for (int b = 0; b < 16; ++b) { const int e = __shfl((b < 8) ? (E0) : (E1), (b & 7) * 8 + grp); SEG[b] = *(const u32x4*)(ub + (size_t)e * DM); } }
; DI void peer_u_phase(const bf16_t* __restrict__ x1, const int* __restrict__ eidx, const unsigned char* __restrict__ U8, float* __restrict__ ph) {
;     ...
;         {
;             const int e0 = eidx[(size_t)t * 128 + lane], e1 = eidx[(size_t)t * 128 + 64 + lane];
;             xa = *(const u32x4*)(xb_ + (size_t)t * DM); xb = *(const u32x4*)(xb_ + (size_t)t * DM + 8);
;             U_ISSUE(sa, e0, e1)
;             if (t + step < T_TOK) { e0n = eidx[(size_t)(t + step) * 128 + lane]; e1n = eidx[(size_t)(t + step) * 128 + 64 + lane]; }
;         }
;         for (; t < T_TOK; t += 2 * step) {
;             int e0nn = 0, e1nn = 0;
;             const bool n1 = t + step < T_TOK, n2 = t + 2 * step < T_TOK, n3 = t + 3 * step < T_TOK;
;             if (n1) { U_ISSUE(sb, e0n, e1n) xan = *(const u32x4*)(xb_ + (size_t)(t + step) * DM); xbn = *(const u32x4*)(xb_ + (size_t)(t + step) * DM + 8); }
;             if (n2) { e0nn = eidx[(size_t)(t + 2 * step) * 128 + lane]; e1nn = eidx[(size_t)(t + 2 * step) * 128 + 64 + lane]; }
;             U_COMPUTE(sa, t)
;             if (n1) {
;                 xa = xan; xb = xbn;
;                 if (n2) { U_ISSUE(sa, e0nn, e1nn) xan = *(const u32x4*)(xb_ + (size_t)(t + 2 * step) * DM); xbn = *(const u32x4*)(xb_ + (size_t)(t + 2 * step) * DM + 8); }
	v_cvt_scalef32_pk_bf16_fp8 v206, v129, 1.0
	v_cvt_scalef32_pk_bf16_fp8 v204, v128, 1.0
	v_cvt_scalef32_pk_bf16_fp8 v205, v128, 1.0 op_sel:[1,0,0]
	v_cvt_scalef32_pk_bf16_fp8 v207, v129, 1.0 op_sel:[1,0,0]
	v_cvt_scalef32_pk_bf16_fp8 v208, v130, 1.0
	v_cvt_scalef32_pk_bf16_fp8 v209, v130, 1.0 op_sel:[1,0,0]
	v_cvt_scalef32_pk_bf16_fp8 v210, v131, 1.0
	v_cvt_scalef32_pk_bf16_fp8 v211, v131, 1.0 op_sel:[1,0,0]
	v_dot2_f32_bf16 v217, v204, v72, 0
	v_dot2_f32_bf16 v217, v205, v73, v217
	v_dot2_f32_bf16 v217, v206, v74, v217
	v_dot2_f32_bf16 v217, v207, v75, v217
	v_dot2_f32_bf16 v217, v208, v140, v217
	v_dot2_f32_bf16 v217, v209, v141, v217
	v_dot2_f32_bf16 v217, v210, v142, v217
	v_dot2_f32_bf16 v217, v211, v143, v217
	s_waitcnt vmcnt(1)
	v_cvt_scalef32_pk_bf16_fp8 v206, v133, 1.0
	v_cvt_scalef32_pk_bf16_fp8 v204, v132, 1.0
	v_cvt_scalef32_pk_bf16_fp8 v205, v132, 1.0 op_sel:[1,0,0]
	v_cvt_scalef32_pk_bf16_fp8 v207, v133, 1.0 op_sel:[1,0,0]
	v_cvt_scalef32_pk_bf16_fp8 v208, v134, 1.0
	v_cvt_scalef32_pk_bf16_fp8 v209, v134, 1.0 op_sel:[1,0,0]
	v_cvt_scalef32_pk_bf16_fp8 v210, v135, 1.0
	v_cvt_scalef32_pk_bf16_fp8 v211, v135, 1.0 op_sel:[1,0,0]
	v_dot2_f32_bf16 v218, v204, v72, 0
	v_dot2_f32_bf16 v218, v205, v73, v218
	v_dot2_f32_bf16 v218, v206, v74, v218
	v_dot2_f32_bf16 v218, v207, v75, v218
	v_dot2_f32_bf16 v218, v208, v140, v218
	v_dot2_f32_bf16 v218, v209, v141, v218
	v_dot2_f32_bf16 v218, v210, v142, v218
	v_dot2_f32_bf16 v218, v211, v143, v218
	s_waitcnt vmcnt(0)
	v_cvt_scalef32_pk_bf16_fp8 v206, v137, 1.0
	v_cvt_scalef32_pk_bf16_fp8 v204, v136, 1.0
	v_cvt_scalef32_pk_bf16_fp8 v205, v136, 1.0 op_sel:[1,0,0]
	v_cvt_scalef32_pk_bf16_fp8 v207, v137, 1.0 op_sel:[1,0,0]
	v_cvt_scalef32_pk_bf16_fp8 v208, v138, 1.0
	v_cvt_scalef32_pk_bf16_fp8 v209, v138, 1.0 op_sel:[1,0,0]
	v_cvt_scalef32_pk_bf16_fp8 v211, v139, 1.0
	v_cvt_scalef32_pk_bf16_fp8 v219, v139, 1.0 op_sel:[1,0,0]
	v_dot2_f32_bf16 v220, v204, v72, 0
	v_dot2_f32_bf16 v220, v205, v73, v220
	v_dot2_f32_bf16 v220, v206, v74, v220
	v_dot2_f32_bf16 v220, v207, v75, v220
	v_dot2_f32_bf16 v220, v208, v140, v220
	v_dot2_f32_bf16 v220, v209, v141, v220
	v_dot2_f32_bf16 v220, v211, v142, v220
	v_dot2_f32_bf16 v220, v219, v143, v220
	v_cndmask_b32_e64 v206, v213, v217, s[8:9]
	ds_bpermute_b32 v206, v193, v206
	v_cndmask_b32_e64 v207, v214, v218, s[8:9]
	v_cndmask_b32_e64 v210, v212, v216, s[8:9]
	ds_bpermute_b32 v207, v193, v207
	v_cndmask_b32_e64 v208, v215, v220, s[8:9]
	ds_bpermute_b32 v210, v193, v210
	ds_bpermute_b32 v208, v193, v208
	v_cndmask_b32_e64 v205, v217, v213, s[8:9]
	s_waitcnt lgkmcnt(3)
	v_add_f32_e32 v205, v205, v206
	v_cndmask_b32_e64 v206, v218, v214, s[8:9]
	v_cndmask_b32_e64 v204, v216, v212, s[8:9]
	s_waitcnt lgkmcnt(2)
	v_add_f32_e32 v206, v206, v207
	v_cndmask_b32_e64 v207, v220, v215, s[8:9]
	s_waitcnt lgkmcnt(1)
	v_add_f32_e32 v204, v204, v210
	s_waitcnt lgkmcnt(0)
	v_add_f32_e32 v207, v207, v208
	v_cndmask_b32_e64 v208, v204, v206, s[10:11]
	v_cndmask_b32_e64 v209, v205, v207, s[10:11]
	ds_bpermute_b32 v208, v194, v208
	ds_bpermute_b32 v209, v194, v209
	v_cndmask_b32_e64 v204, v206, v204, s[10:11]
	v_cndmask_b32_e64 v205, v207, v205, s[10:11]
	v_cndmask_b32_e64 v203, v183, v202, s[12:13]
	s_waitcnt lgkmcnt(1)
	v_add_f32_e32 v204, v204, v208
	s_waitcnt lgkmcnt(0)
	v_add_f32_e32 v205, v205, v209
	ds_bpermute_b32 v203, v195, v203
	v_cndmask_b32_e64 v206, v204, v205, s[12:13]
	ds_bpermute_b32 v206, v195, v206
	v_cndmask_b32_e64 v183, v202, v183, s[12:13]
	s_waitcnt lgkmcnt(1)
	v_add_f32_e32 v207, v183, v203
	v_cndmask_b32_e64 v183, v205, v204, s[12:13]
	s_waitcnt lgkmcnt(0)
	v_add_f32_e32 v204, v183, v206
	s_setprio 0
	v_ashrrev_i32_e32 v183, 31, v182
	v_lshlrev_b64 v[202:203], 12, v[182:183]
	v_lshl_add_u64 v[202:203], v[178:179], 0, v[202:203]
	global_store_dword v[202:203], v207, off
	global_store_dword v[202:203], v204, off offset:256
	s_and_saveexec_b64 s[36:37], s[14:15]
	s_cbranch_execz .LBB0_1228
	v_mov_b64_e32 v[142:143], v[70:71]
	v_mov_b64_e32 v[74:75], v[66:67]
	v_mov_b64_e32 v[140:141], v[68:69]
	v_mov_b64_e32 v[72:73], v[64:65]
	s_and_saveexec_b64 s[0:1], s[16:17]
	s_cbranch_execz .LBB0_1236
	ds_bpermute_b32 v72, v149, v201
	ds_bpermute_b32 v74, v151, v201
	ds_bpermute_b32 v84, v187, v201
	ds_bpermute_b32 v86, v188, v201
	ds_bpermute_b32 v92, v189, v201
	s_waitcnt lgkmcnt(4)
	ds_bpermute_b32 v94, v190, v201
	s_waitcnt lgkmcnt(4)
	v_lshl_add_u32 v72, v72, 7, v252
	ds_bpermute_b32 v100, v191, v201
	v_lshl_add_u32 v74, v74, 7, v252
	s_waitcnt lgkmcnt(4)
	ds_bpermute_b32 v102, v198, v201
	global_load_dwordx4 v[76:79], v72, s[98:99]
	global_load_dwordx4 v[80:83], v74, s[98:99]
	v_lshl_add_u32 v72, v84, 7, v252
	s_waitcnt lgkmcnt(4)
	ds_bpermute_b32 v108, v149, v185
	v_lshl_add_u32 v74, v86, 7, v252
	s_waitcnt lgkmcnt(4)
	ds_bpermute_b32 v110, v151, v185
	global_load_dwordx4 v[84:87], v72, s[98:99]
	global_load_dwordx4 v[88:91], v74, s[98:99]
	v_lshl_add_u32 v72, v92, 7, v252
	s_waitcnt lgkmcnt(4)
	ds_bpermute_b32 v116, v187, v185
	v_lshl_add_u32 v74, v94, 7, v252
	s_waitcnt lgkmcnt(4)
	ds_bpermute_b32 v118, v188, v185
	global_load_dwordx4 v[92:95], v72, s[98:99]
	global_load_dwordx4 v[96:99], v74, s[98:99]
	v_lshl_add_u32 v72, v100, 7, v252
	s_waitcnt lgkmcnt(4)
	ds_bpermute_b32 v124, v189, v185
	v_lshl_add_u32 v74, v102, 7, v252
	s_waitcnt lgkmcnt(4)
	ds_bpermute_b32 v126, v190, v185
	global_load_dwordx4 v[100:103], v72, s[98:99]
	global_load_dwordx4 v[104:107], v74, s[98:99]
	v_lshl_add_u32 v72, v108, 7, v252
	s_waitcnt lgkmcnt(4)
	ds_bpermute_b32 v132, v191, v185
	v_lshl_add_u32 v74, v110, 7, v252
	s_waitcnt lgkmcnt(4)
	ds_bpermute_b32 v134, v198, v185
	global_load_dwordx4 v[108:111], v72, s[98:99]
	global_load_dwordx4 v[112:115], v74, s[98:99]
	v_lshl_add_u32 v72, v116, 7, v252
	s_waitcnt lgkmcnt(4)
	v_lshl_add_u32 v74, v118, 7, v252
	s_waitcnt lgkmcnt(3)
	global_load_dwordx4 v[116:119], v72, s[98:99]
	global_load_dwordx4 v[120:123], v74, s[98:99]
	v_lshl_add_u32 v72, v124, 7, v252
	s_waitcnt lgkmcnt(2)
	v_lshl_add_u32 v74, v126, 7, v252
	s_waitcnt lgkmcnt(1)
	global_load_dwordx4 v[124:127], v72, s[98:99]
	global_load_dwordx4 v[128:131], v74, s[98:99]
	v_lshl_add_u32 v72, v132, 7, v252
	s_waitcnt lgkmcnt(0)
	v_lshl_add_u32 v74, v134, 7, v252
	v_ashrrev_i32_e32 v185, 31, v184
	global_load_dwordx4 v[132:135], v72, s[98:99]
	global_load_dwordx4 v[136:139], v74, s[98:99]
	v_lshlrev_b64 v[72:73], 11, v[184:185]
	v_lshl_add_u64 v[72:73], v[168:169], 0, v[72:73]
	global_load_dwordx4 v[140:143], v[72:73], off offset:16
	s_nop 0
	global_load_dwordx4 v[72:75], v[72:73], off
